# P6 SwiGLU epilogue arithmetic regenerated with adjacent-element packed f32 ops (layers 0-2), same values
# baseline (speedup 1.0000x reference)
.LBB0_751:
	v_mov_b32_e32 v186, 0xbfb8aa3b
	v_mov_b32_e32 v187, 1.0
	s_cmp_eq_u32 s60, s66
	s_movk_i32 s15, 0x200
	s_cselect_b32 s15, s15, 0x300
	s_cmp_lg_u32 s60, s65
	s_cselect_b32 s15, s15, 0x100
	s_cmp_lg_u32 s60, s64
	v_mov_b32_e32 v64, v195
	v_mov_b32_e32 v65, v194
	s_cselect_b32 s15, s15, 0
	s_lshl_b32 s35, s86, 7
	s_or_b32 s35, s35, s78
	v_lshl_add_u32 v66, v64, 5, s82
	v_add_u32_e32 v184, s73, v65
	ds_read_b128 v[72:75], v66
	ds_read_b128 v[52:55], v66 offset:16
	ds_read_b128 v[76:79], v66 offset:256
	ds_read_b128 v[56:59], v66 offset:272
	ds_read_b128 v[202:205], v66 offset:128
	ds_read_b128 v[206:209], v66 offset:384
	ds_read_b128 v[160:163], v66 offset:144
	ds_read_b128 v[164:167], v66 offset:400
	v_lshl_add_u32 v190, v64, 3, s35
	v_add_u32_e32 v64, s15, v184
	v_lshl_add_u32 v64, v64, 3, v199
	ds_read2_b64 v[156:159], v64 offset1:16
	ds_read2_b64 v[136:139], v64 offset0:32 offset1:48
	ds_read2_b64 v[100:103], v64 offset0:128 offset1:144
	ds_read2_b64 v[64:67], v64 offset0:160 offset1:176
	s_waitcnt lgkmcnt(0)
	v_lshl_add_u32 v200, s60, 8, v184
	v_ashrrev_i32_e32 v191, 31, v190
	v_mov_b64_e32 v[184:185], s[42:43]
	v_mad_i64_i32 v[192:193], s[46:47], v200, s83, v[184:185]
	s_andn2_b64 vcc, exec, s[8:9]
	v_pk_fma_f32 v[188:189], v[72:73], v[156:157], v[76:77] op_sel:[0,1,0]
	v_pk_fma_f32 v[210:211], v[74:75], v[156:157], v[78:79] op_sel:[0,1,0]
	v_pk_fma_f32 v[212:213], v[52:53], v[156:157], v[56:57] op_sel:[0,1,0]
	v_pk_fma_f32 v[214:215], v[54:55], v[156:157], v[58:59] op_sel:[0,1,0]
	v_pk_fma_f32 v[216:217], v[202:203], v[156:157], v[206:207] op_sel:[0,1,0]
	v_pk_fma_f32 v[218:219], v[204:205], v[156:157], v[208:209] op_sel:[0,1,0]
	v_pk_fma_f32 v[220:221], v[160:161], v[156:157], v[164:165] op_sel:[0,1,0]
	v_pk_fma_f32 v[222:223], v[162:163], v[156:157], v[166:167] op_sel:[0,1,0]
	v_pk_fma_f32 v[188:189], v[152:153], v[156:157], v[188:189] op_sel_hi:[1,0,1]
	v_pk_fma_f32 v[210:211], v[154:155], v[156:157], v[210:211] op_sel_hi:[1,0,1]
	v_pk_fma_f32 v[212:213], v[144:145], v[156:157], v[212:213] op_sel_hi:[1,0,1]
	v_pk_fma_f32 v[214:215], v[146:147], v[156:157], v[214:215] op_sel_hi:[1,0,1]
	v_pk_fma_f32 v[216:217], v[148:149], v[156:157], v[216:217] op_sel_hi:[1,0,1]
	v_pk_fma_f32 v[218:219], v[150:151], v[156:157], v[218:219] op_sel_hi:[1,0,1]
	v_pk_fma_f32 v[220:221], v[140:141], v[156:157], v[220:221] op_sel_hi:[1,0,1]
	v_pk_fma_f32 v[222:223], v[142:143], v[156:157], v[222:223] op_sel_hi:[1,0,1]
	v_pk_mul_f32 v[224:225], v[188:189], v[186:187] op_sel_hi:[1,0]
	v_pk_mul_f32 v[226:227], v[210:211], v[186:187] op_sel_hi:[1,0]
	v_pk_mul_f32 v[228:229], v[212:213], v[186:187] op_sel_hi:[1,0]
	v_pk_mul_f32 v[230:231], v[214:215], v[186:187] op_sel_hi:[1,0]
	v_exp_f32_e32 v224, v224
	v_exp_f32_e32 v225, v225
	v_exp_f32_e32 v226, v226
	v_exp_f32_e32 v227, v227
	v_exp_f32_e32 v228, v228
	v_exp_f32_e32 v229, v229
	v_exp_f32_e32 v230, v230
	v_exp_f32_e32 v231, v231
	v_pk_add_f32 v[224:225], v[224:225], v[186:187] op_sel:[0,1] op_sel_hi:[1,1]
	v_pk_add_f32 v[226:227], v[226:227], v[186:187] op_sel:[0,1] op_sel_hi:[1,1]
	v_pk_add_f32 v[228:229], v[228:229], v[186:187] op_sel:[0,1] op_sel_hi:[1,1]
	v_pk_add_f32 v[230:231], v[230:231], v[186:187] op_sel:[0,1] op_sel_hi:[1,1]
	v_rcp_f32_e32 v224, v224
	v_rcp_f32_e32 v225, v225
	v_rcp_f32_e32 v226, v226
	v_rcp_f32_e32 v227, v227
	v_rcp_f32_e32 v228, v228
	v_rcp_f32_e32 v229, v229
	v_rcp_f32_e32 v230, v230
	v_rcp_f32_e32 v231, v231
	v_pk_mul_f32 v[224:225], v[188:189], v[224:225]
	v_pk_mul_f32 v[226:227], v[210:211], v[226:227]
	v_pk_mul_f32 v[228:229], v[212:213], v[228:229]
	v_pk_mul_f32 v[230:231], v[214:215], v[230:231]
	v_pk_mul_f32 v[216:217], v[216:217], v[224:225]
	v_pk_mul_f32 v[218:219], v[218:219], v[226:227]
	v_pk_mul_f32 v[220:221], v[220:221], v[228:229]
	v_pk_mul_f32 v[222:223], v[222:223], v[230:231]
	v_cvt_pk_bf16_f32 v232, v216, v217
	v_cvt_pk_bf16_f32 v233, v218, v219
	v_cvt_pk_bf16_f32 v234, v220, v221
	v_cvt_pk_bf16_f32 v235, v222, v223
	v_lshlrev_b64 v[142:143], 1, v[190:191]
	v_lshl_add_u64 v[146:147], v[192:193], 0, v[142:143]
	global_store_dwordx4 v[146:147], v[232:235], off
	v_add_u32_e32 v146, 16, v200
	v_mad_i64_i32 v[146:147], s[46:47], v146, s83, v[184:185]
	v_pk_fma_f32 v[188:189], v[72:73], v[158:159], v[76:77] op_sel:[0,1,0]
	v_pk_fma_f32 v[210:211], v[74:75], v[158:159], v[78:79] op_sel:[0,1,0]
	v_pk_fma_f32 v[212:213], v[52:53], v[158:159], v[56:57] op_sel:[0,1,0]
	v_pk_fma_f32 v[214:215], v[54:55], v[158:159], v[58:59] op_sel:[0,1,0]
	v_pk_fma_f32 v[216:217], v[202:203], v[158:159], v[206:207] op_sel:[0,1,0]
	v_pk_fma_f32 v[218:219], v[204:205], v[158:159], v[208:209] op_sel:[0,1,0]
	v_pk_fma_f32 v[220:221], v[160:161], v[158:159], v[164:165] op_sel:[0,1,0]
	v_pk_fma_f32 v[222:223], v[162:163], v[158:159], v[166:167] op_sel:[0,1,0]
	v_pk_fma_f32 v[188:189], v[132:133], v[158:159], v[188:189] op_sel_hi:[1,0,1]
	v_pk_fma_f32 v[210:211], v[134:135], v[158:159], v[210:211] op_sel_hi:[1,0,1]
	v_pk_fma_f32 v[212:213], v[124:125], v[158:159], v[212:213] op_sel_hi:[1,0,1]
	v_pk_fma_f32 v[214:215], v[126:127], v[158:159], v[214:215] op_sel_hi:[1,0,1]
	v_pk_fma_f32 v[216:217], v[128:129], v[158:159], v[216:217] op_sel_hi:[1,0,1]
	v_pk_fma_f32 v[218:219], v[130:131], v[158:159], v[218:219] op_sel_hi:[1,0,1]
	v_pk_fma_f32 v[220:221], v[120:121], v[158:159], v[220:221] op_sel_hi:[1,0,1]
	v_pk_fma_f32 v[222:223], v[122:123], v[158:159], v[222:223] op_sel_hi:[1,0,1]
	v_pk_mul_f32 v[224:225], v[188:189], v[186:187] op_sel_hi:[1,0]
	v_pk_mul_f32 v[226:227], v[210:211], v[186:187] op_sel_hi:[1,0]
	v_pk_mul_f32 v[228:229], v[212:213], v[186:187] op_sel_hi:[1,0]
	v_pk_mul_f32 v[230:231], v[214:215], v[186:187] op_sel_hi:[1,0]
	v_exp_f32_e32 v224, v224
	v_exp_f32_e32 v225, v225
	v_exp_f32_e32 v226, v226
	v_exp_f32_e32 v227, v227
	v_exp_f32_e32 v228, v228
	v_exp_f32_e32 v229, v229
	v_exp_f32_e32 v230, v230
	v_exp_f32_e32 v231, v231
	v_pk_add_f32 v[224:225], v[224:225], v[186:187] op_sel:[0,1] op_sel_hi:[1,1]
	v_pk_add_f32 v[226:227], v[226:227], v[186:187] op_sel:[0,1] op_sel_hi:[1,1]
	v_pk_add_f32 v[228:229], v[228:229], v[186:187] op_sel:[0,1] op_sel_hi:[1,1]
	v_pk_add_f32 v[230:231], v[230:231], v[186:187] op_sel:[0,1] op_sel_hi:[1,1]
	v_rcp_f32_e32 v224, v224
	v_rcp_f32_e32 v225, v225
	v_rcp_f32_e32 v226, v226
	v_rcp_f32_e32 v227, v227
	v_rcp_f32_e32 v228, v228
	v_rcp_f32_e32 v229, v229
	v_rcp_f32_e32 v230, v230
	v_rcp_f32_e32 v231, v231
	v_pk_mul_f32 v[224:225], v[188:189], v[224:225]
	v_pk_mul_f32 v[226:227], v[210:211], v[226:227]
	v_pk_mul_f32 v[228:229], v[212:213], v[228:229]
	v_pk_mul_f32 v[230:231], v[214:215], v[230:231]
	v_pk_mul_f32 v[216:217], v[216:217], v[224:225]
	v_pk_mul_f32 v[218:219], v[218:219], v[226:227]
	v_pk_mul_f32 v[220:221], v[220:221], v[228:229]
	v_pk_mul_f32 v[222:223], v[222:223], v[230:231]
	v_cvt_pk_bf16_f32 v236, v216, v217
	v_cvt_pk_bf16_f32 v237, v218, v219
	v_cvt_pk_bf16_f32 v238, v220, v221
	v_cvt_pk_bf16_f32 v239, v222, v223
	v_lshl_add_u64 v[124:125], v[146:147], 0, v[142:143]
	global_store_dwordx4 v[124:125], v[236:239], off
	v_add_u32_e32 v120, 32, v200
	v_mad_i64_i32 v[120:121], s[46:47], v120, s83, v[184:185]
	v_pk_fma_f32 v[188:189], v[72:73], v[136:137], v[76:77] op_sel:[0,1,0]
	v_pk_fma_f32 v[210:211], v[74:75], v[136:137], v[78:79] op_sel:[0,1,0]
	v_pk_fma_f32 v[212:213], v[52:53], v[136:137], v[56:57] op_sel:[0,1,0]
	v_pk_fma_f32 v[214:215], v[54:55], v[136:137], v[58:59] op_sel:[0,1,0]
	v_pk_fma_f32 v[216:217], v[202:203], v[136:137], v[206:207] op_sel:[0,1,0]
	v_pk_fma_f32 v[218:219], v[204:205], v[136:137], v[208:209] op_sel:[0,1,0]
	v_pk_fma_f32 v[220:221], v[160:161], v[136:137], v[164:165] op_sel:[0,1,0]
	v_pk_fma_f32 v[222:223], v[162:163], v[136:137], v[166:167] op_sel:[0,1,0]
	v_pk_fma_f32 v[188:189], v[116:117], v[136:137], v[188:189] op_sel_hi:[1,0,1]
	v_pk_fma_f32 v[210:211], v[118:119], v[136:137], v[210:211] op_sel_hi:[1,0,1]
	v_pk_fma_f32 v[212:213], v[108:109], v[136:137], v[212:213] op_sel_hi:[1,0,1]
	v_pk_fma_f32 v[214:215], v[110:111], v[136:137], v[214:215] op_sel_hi:[1,0,1]
	v_pk_fma_f32 v[216:217], v[112:113], v[136:137], v[216:217] op_sel_hi:[1,0,1]
	v_pk_fma_f32 v[218:219], v[114:115], v[136:137], v[218:219] op_sel_hi:[1,0,1]
	v_pk_fma_f32 v[220:221], v[104:105], v[136:137], v[220:221] op_sel_hi:[1,0,1]
	v_pk_fma_f32 v[222:223], v[106:107], v[136:137], v[222:223] op_sel_hi:[1,0,1]
	v_pk_mul_f32 v[224:225], v[188:189], v[186:187] op_sel_hi:[1,0]
	v_pk_mul_f32 v[226:227], v[210:211], v[186:187] op_sel_hi:[1,0]
	v_pk_mul_f32 v[228:229], v[212:213], v[186:187] op_sel_hi:[1,0]
	v_pk_mul_f32 v[230:231], v[214:215], v[186:187] op_sel_hi:[1,0]
	v_exp_f32_e32 v224, v224
	v_exp_f32_e32 v225, v225
	v_exp_f32_e32 v226, v226
	v_exp_f32_e32 v227, v227
	v_exp_f32_e32 v228, v228
	v_exp_f32_e32 v229, v229
	v_exp_f32_e32 v230, v230
	v_exp_f32_e32 v231, v231
	v_pk_add_f32 v[224:225], v[224:225], v[186:187] op_sel:[0,1] op_sel_hi:[1,1]
	v_pk_add_f32 v[226:227], v[226:227], v[186:187] op_sel:[0,1] op_sel_hi:[1,1]
	v_pk_add_f32 v[228:229], v[228:229], v[186:187] op_sel:[0,1] op_sel_hi:[1,1]
	v_pk_add_f32 v[230:231], v[230:231], v[186:187] op_sel:[0,1] op_sel_hi:[1,1]
	v_rcp_f32_e32 v224, v224
	v_rcp_f32_e32 v225, v225
	v_rcp_f32_e32 v226, v226
	v_rcp_f32_e32 v227, v227
	v_rcp_f32_e32 v228, v228
	v_rcp_f32_e32 v229, v229
	v_rcp_f32_e32 v230, v230
	v_rcp_f32_e32 v231, v231
	v_pk_mul_f32 v[224:225], v[188:189], v[224:225]
	v_pk_mul_f32 v[226:227], v[210:211], v[226:227]
	v_pk_mul_f32 v[228:229], v[212:213], v[228:229]
	v_pk_mul_f32 v[230:231], v[214:215], v[230:231]
	v_pk_mul_f32 v[216:217], v[216:217], v[224:225]
	v_pk_mul_f32 v[218:219], v[218:219], v[226:227]
	v_pk_mul_f32 v[220:221], v[220:221], v[228:229]
	v_pk_mul_f32 v[222:223], v[222:223], v[230:231]
	v_cvt_pk_bf16_f32 v240, v216, v217
	v_cvt_pk_bf16_f32 v241, v218, v219
	v_cvt_pk_bf16_f32 v242, v220, v221
	v_cvt_pk_bf16_f32 v243, v222, v223
	v_lshl_add_u64 v[108:109], v[120:121], 0, v[142:143]
	global_store_dwordx4 v[108:109], v[240:243], off
	v_add_u32_e32 v104, 48, v200
	v_mad_i64_i32 v[104:105], s[46:47], v104, s83, v[184:185]
	v_pk_fma_f32 v[188:189], v[72:73], v[138:139], v[76:77] op_sel:[0,1,0]
	v_pk_fma_f32 v[210:211], v[74:75], v[138:139], v[78:79] op_sel:[0,1,0]
	v_pk_fma_f32 v[212:213], v[52:53], v[138:139], v[56:57] op_sel:[0,1,0]
	v_pk_fma_f32 v[214:215], v[54:55], v[138:139], v[58:59] op_sel:[0,1,0]
	v_pk_fma_f32 v[216:217], v[202:203], v[138:139], v[206:207] op_sel:[0,1,0]
	v_pk_fma_f32 v[218:219], v[204:205], v[138:139], v[208:209] op_sel:[0,1,0]
	v_pk_fma_f32 v[220:221], v[160:161], v[138:139], v[164:165] op_sel:[0,1,0]
	v_pk_fma_f32 v[222:223], v[162:163], v[138:139], v[166:167] op_sel:[0,1,0]
	v_pk_fma_f32 v[188:189], v[96:97], v[138:139], v[188:189] op_sel_hi:[1,0,1]
	v_pk_fma_f32 v[210:211], v[98:99], v[138:139], v[210:211] op_sel_hi:[1,0,1]
	v_pk_fma_f32 v[212:213], v[88:89], v[138:139], v[212:213] op_sel_hi:[1,0,1]
	v_pk_fma_f32 v[214:215], v[90:91], v[138:139], v[214:215] op_sel_hi:[1,0,1]
	v_pk_fma_f32 v[216:217], v[92:93], v[138:139], v[216:217] op_sel_hi:[1,0,1]
	v_pk_fma_f32 v[218:219], v[94:95], v[138:139], v[218:219] op_sel_hi:[1,0,1]
	v_pk_fma_f32 v[220:221], v[84:85], v[138:139], v[220:221] op_sel_hi:[1,0,1]
	v_pk_fma_f32 v[222:223], v[86:87], v[138:139], v[222:223] op_sel_hi:[1,0,1]
	v_pk_mul_f32 v[224:225], v[188:189], v[186:187] op_sel_hi:[1,0]
	v_pk_mul_f32 v[226:227], v[210:211], v[186:187] op_sel_hi:[1,0]
	v_pk_mul_f32 v[228:229], v[212:213], v[186:187] op_sel_hi:[1,0]
	v_pk_mul_f32 v[230:231], v[214:215], v[186:187] op_sel_hi:[1,0]
	v_exp_f32_e32 v224, v224
	v_exp_f32_e32 v225, v225
	v_exp_f32_e32 v226, v226
	v_exp_f32_e32 v227, v227
	v_exp_f32_e32 v228, v228
	v_exp_f32_e32 v229, v229
	v_exp_f32_e32 v230, v230
	v_exp_f32_e32 v231, v231
	v_pk_add_f32 v[224:225], v[224:225], v[186:187] op_sel:[0,1] op_sel_hi:[1,1]
	v_pk_add_f32 v[226:227], v[226:227], v[186:187] op_sel:[0,1] op_sel_hi:[1,1]
	v_pk_add_f32 v[228:229], v[228:229], v[186:187] op_sel:[0,1] op_sel_hi:[1,1]
	v_pk_add_f32 v[230:231], v[230:231], v[186:187] op_sel:[0,1] op_sel_hi:[1,1]
	v_rcp_f32_e32 v224, v224
	v_rcp_f32_e32 v225, v225
	v_rcp_f32_e32 v226, v226
	v_rcp_f32_e32 v227, v227
	v_rcp_f32_e32 v228, v228
	v_rcp_f32_e32 v229, v229
	v_rcp_f32_e32 v230, v230
	v_rcp_f32_e32 v231, v231
	v_pk_mul_f32 v[224:225], v[188:189], v[224:225]
	v_pk_mul_f32 v[226:227], v[210:211], v[226:227]
	v_pk_mul_f32 v[228:229], v[212:213], v[228:229]
	v_pk_mul_f32 v[230:231], v[214:215], v[230:231]
	v_pk_mul_f32 v[216:217], v[216:217], v[224:225]
	v_pk_mul_f32 v[218:219], v[218:219], v[226:227]
	v_pk_mul_f32 v[220:221], v[220:221], v[228:229]
	v_pk_mul_f32 v[222:223], v[222:223], v[230:231]
	v_cvt_pk_bf16_f32 v244, v216, v217
	v_cvt_pk_bf16_f32 v245, v218, v219
	v_cvt_pk_bf16_f32 v246, v220, v221
	v_cvt_pk_bf16_f32 v247, v222, v223
	v_lshl_add_u64 v[88:89], v[104:105], 0, v[142:143]
	global_store_dwordx4 v[88:89], v[244:247], off
	v_add_u32_e32 v84, 0x80, v200
	v_mad_i64_i32 v[84:85], s[46:47], v84, s83, v[184:185]
	v_pk_fma_f32 v[188:189], v[72:73], v[100:101], v[76:77] op_sel:[0,1,0]
	v_pk_fma_f32 v[210:211], v[74:75], v[100:101], v[78:79] op_sel:[0,1,0]
	v_pk_fma_f32 v[212:213], v[52:53], v[100:101], v[56:57] op_sel:[0,1,0]
	v_pk_fma_f32 v[214:215], v[54:55], v[100:101], v[58:59] op_sel:[0,1,0]
	v_pk_fma_f32 v[216:217], v[202:203], v[100:101], v[206:207] op_sel:[0,1,0]
	v_pk_fma_f32 v[218:219], v[204:205], v[100:101], v[208:209] op_sel:[0,1,0]
	v_pk_fma_f32 v[220:221], v[160:161], v[100:101], v[164:165] op_sel:[0,1,0]
	v_pk_fma_f32 v[222:223], v[162:163], v[100:101], v[166:167] op_sel:[0,1,0]
	v_pk_fma_f32 v[188:189], v[80:81], v[100:101], v[188:189] op_sel_hi:[1,0,1]
	v_pk_fma_f32 v[210:211], v[82:83], v[100:101], v[210:211] op_sel_hi:[1,0,1]
	v_pk_fma_f32 v[212:213], v[60:61], v[100:101], v[212:213] op_sel_hi:[1,0,1]
	v_pk_fma_f32 v[214:215], v[62:63], v[100:101], v[214:215] op_sel_hi:[1,0,1]
	v_pk_fma_f32 v[216:217], v[68:69], v[100:101], v[216:217] op_sel_hi:[1,0,1]
	v_pk_fma_f32 v[218:219], v[70:71], v[100:101], v[218:219] op_sel_hi:[1,0,1]
	v_pk_fma_f32 v[220:221], v[48:49], v[100:101], v[220:221] op_sel_hi:[1,0,1]
	v_pk_fma_f32 v[222:223], v[50:51], v[100:101], v[222:223] op_sel_hi:[1,0,1]
	v_pk_mul_f32 v[224:225], v[188:189], v[186:187] op_sel_hi:[1,0]
	v_pk_mul_f32 v[226:227], v[210:211], v[186:187] op_sel_hi:[1,0]
	v_pk_mul_f32 v[228:229], v[212:213], v[186:187] op_sel_hi:[1,0]
	v_pk_mul_f32 v[230:231], v[214:215], v[186:187] op_sel_hi:[1,0]
	v_exp_f32_e32 v224, v224
	v_exp_f32_e32 v225, v225
	v_exp_f32_e32 v226, v226
	v_exp_f32_e32 v227, v227
	v_exp_f32_e32 v228, v228
	v_exp_f32_e32 v229, v229
	v_exp_f32_e32 v230, v230
	v_exp_f32_e32 v231, v231
	v_pk_add_f32 v[224:225], v[224:225], v[186:187] op_sel:[0,1] op_sel_hi:[1,1]
	v_pk_add_f32 v[226:227], v[226:227], v[186:187] op_sel:[0,1] op_sel_hi:[1,1]
	v_pk_add_f32 v[228:229], v[228:229], v[186:187] op_sel:[0,1] op_sel_hi:[1,1]
	v_pk_add_f32 v[230:231], v[230:231], v[186:187] op_sel:[0,1] op_sel_hi:[1,1]
	v_rcp_f32_e32 v224, v224
	v_rcp_f32_e32 v225, v225
	v_rcp_f32_e32 v226, v226
	v_rcp_f32_e32 v227, v227
	v_rcp_f32_e32 v228, v228
	v_rcp_f32_e32 v229, v229
	v_rcp_f32_e32 v230, v230
	v_rcp_f32_e32 v231, v231
	v_pk_mul_f32 v[224:225], v[188:189], v[224:225]
	v_pk_mul_f32 v[226:227], v[210:211], v[226:227]
	v_pk_mul_f32 v[228:229], v[212:213], v[228:229]
	v_pk_mul_f32 v[230:231], v[214:215], v[230:231]
	v_pk_mul_f32 v[216:217], v[216:217], v[224:225]
	v_pk_mul_f32 v[218:219], v[218:219], v[226:227]
	v_pk_mul_f32 v[220:221], v[220:221], v[228:229]
	v_pk_mul_f32 v[222:223], v[222:223], v[230:231]
	v_cvt_pk_bf16_f32 v248, v216, v217
	v_cvt_pk_bf16_f32 v249, v218, v219
	v_cvt_pk_bf16_f32 v250, v220, v221
	v_cvt_pk_bf16_f32 v251, v222, v223
	v_lshl_add_u64 v[60:61], v[84:85], 0, v[142:143]
	global_store_dwordx4 v[60:61], v[248:251], off
	v_add_u32_e32 v48, 0x90, v200
	v_mad_i64_i32 v[48:49], s[46:47], v48, s83, v[184:185]
	v_pk_fma_f32 v[188:189], v[72:73], v[102:103], v[76:77] op_sel:[0,1,0]
	v_pk_fma_f32 v[210:211], v[74:75], v[102:103], v[78:79] op_sel:[0,1,0]
	v_pk_fma_f32 v[212:213], v[52:53], v[102:103], v[56:57] op_sel:[0,1,0]
	v_pk_fma_f32 v[214:215], v[54:55], v[102:103], v[58:59] op_sel:[0,1,0]
	v_pk_fma_f32 v[216:217], v[202:203], v[102:103], v[206:207] op_sel:[0,1,0]
	v_pk_fma_f32 v[218:219], v[204:205], v[102:103], v[208:209] op_sel:[0,1,0]
	v_pk_fma_f32 v[220:221], v[160:161], v[102:103], v[164:165] op_sel:[0,1,0]
	v_pk_fma_f32 v[222:223], v[162:163], v[102:103], v[166:167] op_sel:[0,1,0]
	v_pk_fma_f32 v[188:189], v[44:45], v[102:103], v[188:189] op_sel_hi:[1,0,1]
	v_pk_fma_f32 v[210:211], v[46:47], v[102:103], v[210:211] op_sel_hi:[1,0,1]
	v_pk_fma_f32 v[212:213], v[36:37], v[102:103], v[212:213] op_sel_hi:[1,0,1]
	v_pk_fma_f32 v[214:215], v[38:39], v[102:103], v[214:215] op_sel_hi:[1,0,1]
	v_pk_fma_f32 v[216:217], v[40:41], v[102:103], v[216:217] op_sel_hi:[1,0,1]
	v_pk_fma_f32 v[218:219], v[42:43], v[102:103], v[218:219] op_sel_hi:[1,0,1]
	v_pk_fma_f32 v[220:221], v[32:33], v[102:103], v[220:221] op_sel_hi:[1,0,1]
	v_pk_fma_f32 v[222:223], v[34:35], v[102:103], v[222:223] op_sel_hi:[1,0,1]
	v_pk_mul_f32 v[224:225], v[188:189], v[186:187] op_sel_hi:[1,0]
	v_pk_mul_f32 v[226:227], v[210:211], v[186:187] op_sel_hi:[1,0]
	v_pk_mul_f32 v[228:229], v[212:213], v[186:187] op_sel_hi:[1,0]
	v_pk_mul_f32 v[230:231], v[214:215], v[186:187] op_sel_hi:[1,0]
	v_exp_f32_e32 v224, v224
	v_exp_f32_e32 v225, v225
	v_exp_f32_e32 v226, v226
	v_exp_f32_e32 v227, v227
	v_exp_f32_e32 v228, v228
	v_exp_f32_e32 v229, v229
	v_exp_f32_e32 v230, v230
	v_exp_f32_e32 v231, v231
	v_pk_add_f32 v[224:225], v[224:225], v[186:187] op_sel:[0,1] op_sel_hi:[1,1]
	v_pk_add_f32 v[226:227], v[226:227], v[186:187] op_sel:[0,1] op_sel_hi:[1,1]
	v_pk_add_f32 v[228:229], v[228:229], v[186:187] op_sel:[0,1] op_sel_hi:[1,1]
	v_pk_add_f32 v[230:231], v[230:231], v[186:187] op_sel:[0,1] op_sel_hi:[1,1]
	v_rcp_f32_e32 v224, v224
	v_rcp_f32_e32 v225, v225
	v_rcp_f32_e32 v226, v226
	v_rcp_f32_e32 v227, v227
	v_rcp_f32_e32 v228, v228
	v_rcp_f32_e32 v229, v229
	v_rcp_f32_e32 v230, v230
	v_rcp_f32_e32 v231, v231
	v_pk_mul_f32 v[224:225], v[188:189], v[224:225]
	v_pk_mul_f32 v[226:227], v[210:211], v[226:227]
	v_pk_mul_f32 v[228:229], v[212:213], v[228:229]
	v_pk_mul_f32 v[230:231], v[214:215], v[230:231]
	v_pk_mul_f32 v[216:217], v[216:217], v[224:225]
	v_pk_mul_f32 v[218:219], v[218:219], v[226:227]
	v_pk_mul_f32 v[220:221], v[220:221], v[228:229]
	v_pk_mul_f32 v[222:223], v[222:223], v[230:231]
	v_cvt_pk_bf16_f32 v232, v216, v217
	v_cvt_pk_bf16_f32 v233, v218, v219
	v_cvt_pk_bf16_f32 v234, v220, v221
	v_cvt_pk_bf16_f32 v235, v222, v223
	v_lshl_add_u64 v[36:37], v[48:49], 0, v[142:143]
	global_store_dwordx4 v[36:37], v[232:235], off
	v_add_u32_e32 v32, 0xa0, v200
	v_mad_i64_i32 v[32:33], s[46:47], v32, s83, v[184:185]
	v_pk_fma_f32 v[188:189], v[72:73], v[64:65], v[76:77] op_sel:[0,1,0]
	v_pk_fma_f32 v[210:211], v[74:75], v[64:65], v[78:79] op_sel:[0,1,0]
	v_pk_fma_f32 v[212:213], v[52:53], v[64:65], v[56:57] op_sel:[0,1,0]
	v_pk_fma_f32 v[214:215], v[54:55], v[64:65], v[58:59] op_sel:[0,1,0]
	v_pk_fma_f32 v[216:217], v[202:203], v[64:65], v[206:207] op_sel:[0,1,0]
	v_pk_fma_f32 v[218:219], v[204:205], v[64:65], v[208:209] op_sel:[0,1,0]
	v_pk_fma_f32 v[220:221], v[160:161], v[64:65], v[164:165] op_sel:[0,1,0]
	v_pk_fma_f32 v[222:223], v[162:163], v[64:65], v[166:167] op_sel:[0,1,0]
	v_pk_fma_f32 v[188:189], v[28:29], v[64:65], v[188:189] op_sel_hi:[1,0,1]
	v_pk_fma_f32 v[210:211], v[30:31], v[64:65], v[210:211] op_sel_hi:[1,0,1]
	v_pk_fma_f32 v[212:213], v[20:21], v[64:65], v[212:213] op_sel_hi:[1,0,1]
	v_pk_fma_f32 v[214:215], v[22:23], v[64:65], v[214:215] op_sel_hi:[1,0,1]
	v_pk_fma_f32 v[216:217], v[24:25], v[64:65], v[216:217] op_sel_hi:[1,0,1]
	v_pk_fma_f32 v[218:219], v[26:27], v[64:65], v[218:219] op_sel_hi:[1,0,1]
	v_pk_fma_f32 v[220:221], v[16:17], v[64:65], v[220:221] op_sel_hi:[1,0,1]
	v_pk_fma_f32 v[222:223], v[18:19], v[64:65], v[222:223] op_sel_hi:[1,0,1]
	v_pk_mul_f32 v[224:225], v[188:189], v[186:187] op_sel_hi:[1,0]
	v_pk_mul_f32 v[226:227], v[210:211], v[186:187] op_sel_hi:[1,0]
	v_pk_mul_f32 v[228:229], v[212:213], v[186:187] op_sel_hi:[1,0]
	v_pk_mul_f32 v[230:231], v[214:215], v[186:187] op_sel_hi:[1,0]
	v_exp_f32_e32 v224, v224
	v_exp_f32_e32 v225, v225
	v_exp_f32_e32 v226, v226
	v_exp_f32_e32 v227, v227
	v_exp_f32_e32 v228, v228
	v_exp_f32_e32 v229, v229
	v_exp_f32_e32 v230, v230
	v_exp_f32_e32 v231, v231
	v_pk_add_f32 v[224:225], v[224:225], v[186:187] op_sel:[0,1] op_sel_hi:[1,1]
	v_pk_add_f32 v[226:227], v[226:227], v[186:187] op_sel:[0,1] op_sel_hi:[1,1]
	v_pk_add_f32 v[228:229], v[228:229], v[186:187] op_sel:[0,1] op_sel_hi:[1,1]
	v_pk_add_f32 v[230:231], v[230:231], v[186:187] op_sel:[0,1] op_sel_hi:[1,1]
	v_rcp_f32_e32 v224, v224
	v_rcp_f32_e32 v225, v225
	v_rcp_f32_e32 v226, v226
	v_rcp_f32_e32 v227, v227
	v_rcp_f32_e32 v228, v228
	v_rcp_f32_e32 v229, v229
	v_rcp_f32_e32 v230, v230
	v_rcp_f32_e32 v231, v231
	v_pk_mul_f32 v[224:225], v[188:189], v[224:225]
	v_pk_mul_f32 v[226:227], v[210:211], v[226:227]
	v_pk_mul_f32 v[228:229], v[212:213], v[228:229]
	v_pk_mul_f32 v[230:231], v[214:215], v[230:231]
	v_pk_mul_f32 v[216:217], v[216:217], v[224:225]
	v_pk_mul_f32 v[218:219], v[218:219], v[226:227]
	v_pk_mul_f32 v[220:221], v[220:221], v[228:229]
	v_pk_mul_f32 v[222:223], v[222:223], v[230:231]
	v_cvt_pk_bf16_f32 v236, v216, v217
	v_cvt_pk_bf16_f32 v237, v218, v219
	v_cvt_pk_bf16_f32 v238, v220, v221
	v_cvt_pk_bf16_f32 v239, v222, v223
	v_lshl_add_u64 v[20:21], v[32:33], 0, v[142:143]
	global_store_dwordx4 v[20:21], v[236:239], off
	v_add_u32_e32 v16, 0xb0, v200
	v_mad_i64_i32 v[16:17], s[46:47], v16, s83, v[184:185]
	s_nop 1
	s_mov_b64 s[46:47], -1
	v_pk_fma_f32 v[188:189], v[72:73], v[66:67], v[76:77] op_sel:[0,1,0]
	v_pk_fma_f32 v[210:211], v[74:75], v[66:67], v[78:79] op_sel:[0,1,0]
	v_pk_fma_f32 v[212:213], v[52:53], v[66:67], v[56:57] op_sel:[0,1,0]
	v_pk_fma_f32 v[214:215], v[54:55], v[66:67], v[58:59] op_sel:[0,1,0]
	v_pk_fma_f32 v[216:217], v[202:203], v[66:67], v[206:207] op_sel:[0,1,0]
	v_pk_fma_f32 v[218:219], v[204:205], v[66:67], v[208:209] op_sel:[0,1,0]
	v_pk_fma_f32 v[220:221], v[160:161], v[66:67], v[164:165] op_sel:[0,1,0]
	v_pk_fma_f32 v[222:223], v[162:163], v[66:67], v[166:167] op_sel:[0,1,0]
	v_pk_fma_f32 v[188:189], v[12:13], v[66:67], v[188:189] op_sel_hi:[1,0,1]
	v_pk_fma_f32 v[210:211], v[14:15], v[66:67], v[210:211] op_sel_hi:[1,0,1]
	v_pk_fma_f32 v[212:213], v[4:5], v[66:67], v[212:213] op_sel_hi:[1,0,1]
	v_pk_fma_f32 v[214:215], v[6:7], v[66:67], v[214:215] op_sel_hi:[1,0,1]
	v_pk_fma_f32 v[216:217], v[8:9], v[66:67], v[216:217] op_sel_hi:[1,0,1]
	v_pk_fma_f32 v[218:219], v[10:11], v[66:67], v[218:219] op_sel_hi:[1,0,1]
	v_pk_fma_f32 v[220:221], v[0:1], v[66:67], v[220:221] op_sel_hi:[1,0,1]
	v_pk_fma_f32 v[222:223], v[2:3], v[66:67], v[222:223] op_sel_hi:[1,0,1]
	v_pk_mul_f32 v[224:225], v[188:189], v[186:187] op_sel_hi:[1,0]
	v_pk_mul_f32 v[226:227], v[210:211], v[186:187] op_sel_hi:[1,0]
	v_pk_mul_f32 v[228:229], v[212:213], v[186:187] op_sel_hi:[1,0]
	v_pk_mul_f32 v[230:231], v[214:215], v[186:187] op_sel_hi:[1,0]
	v_exp_f32_e32 v224, v224
	v_exp_f32_e32 v225, v225
	v_exp_f32_e32 v226, v226
	v_exp_f32_e32 v227, v227
	v_exp_f32_e32 v228, v228
	v_exp_f32_e32 v229, v229
	v_exp_f32_e32 v230, v230
	v_exp_f32_e32 v231, v231
	v_pk_add_f32 v[224:225], v[224:225], v[186:187] op_sel:[0,1] op_sel_hi:[1,1]
	v_pk_add_f32 v[226:227], v[226:227], v[186:187] op_sel:[0,1] op_sel_hi:[1,1]
	v_pk_add_f32 v[228:229], v[228:229], v[186:187] op_sel:[0,1] op_sel_hi:[1,1]
	v_pk_add_f32 v[230:231], v[230:231], v[186:187] op_sel:[0,1] op_sel_hi:[1,1]
	v_rcp_f32_e32 v224, v224
	v_rcp_f32_e32 v225, v225
	v_rcp_f32_e32 v226, v226
	v_rcp_f32_e32 v227, v227
	v_rcp_f32_e32 v228, v228
	v_rcp_f32_e32 v229, v229
	v_rcp_f32_e32 v230, v230
	v_rcp_f32_e32 v231, v231
	v_pk_mul_f32 v[224:225], v[188:189], v[224:225]
	v_pk_mul_f32 v[226:227], v[210:211], v[226:227]
	v_pk_mul_f32 v[228:229], v[212:213], v[228:229]
	v_pk_mul_f32 v[230:231], v[214:215], v[230:231]
	v_pk_mul_f32 v[216:217], v[216:217], v[224:225]
	v_pk_mul_f32 v[218:219], v[218:219], v[226:227]
	v_pk_mul_f32 v[220:221], v[220:221], v[228:229]
	v_pk_mul_f32 v[222:223], v[222:223], v[230:231]
	v_cvt_pk_bf16_f32 v240, v216, v217
	v_cvt_pk_bf16_f32 v241, v218, v219
	v_cvt_pk_bf16_f32 v242, v220, v221
	v_cvt_pk_bf16_f32 v243, v222, v223
	v_lshl_add_u64 v[4:5], v[16:17], 0, v[142:143]
	global_store_dwordx4 v[4:5], v[240:243], off
	s_mov_b32 s99, 1
	s_cbranch_vccnz .LBB0_742
	s_andn2_b64 vcc, exec, s[0:1]
	s_cbranch_vccnz .LBB0_741
	s_barrier
	s_branch .LBB0_741

.LBB0_1611:
	v_mov_b32_e32 v186, 0xbfb8aa3b
	v_mov_b32_e32 v187, 1.0
	s_cmp_eq_u32 s40, s66
	s_movk_i32 s15, 0x200
	s_cselect_b32 s15, s15, 0x300
	s_cmp_lg_u32 s40, s65
	v_mov_b32_e32 v64, v194
	v_mov_b32_e32 v65, v195
	s_cselect_b32 s15, s15, 0x100
	s_cmp_lg_u32 s40, s64
	s_cselect_b32 s15, s15, 0
	v_lshl_add_u32 v66, v65, 5, s85
	v_add_u32_e32 v184, s78, v64
	ds_read_b128 v[72:75], v66
	ds_read_b128 v[52:55], v66 offset:16
	ds_read_b128 v[76:79], v66 offset:256
	ds_read_b128 v[56:59], v66 offset:272
	ds_read_b128 v[202:205], v66 offset:128
	ds_read_b128 v[206:209], v66 offset:384
	ds_read_b128 v[160:163], v66 offset:144
	ds_read_b128 v[164:167], v66 offset:400
	s_lshl_b32 s35, s41, 7
	v_add_u32_e32 v64, s15, v184
	s_or_b32 s35, s35, s79
	v_lshl_add_u32 v64, v64, 3, v199
	v_lshl_add_u32 v190, v65, 3, s35
	ds_read2_b64 v[156:159], v64 offset1:16
	ds_read2_b64 v[136:139], v64 offset0:32 offset1:48
	ds_read2_b64 v[100:103], v64 offset0:128 offset1:144
	ds_read2_b64 v[64:67], v64 offset0:160 offset1:176
	s_waitcnt lgkmcnt(0)
	v_lshl_add_u32 v200, s40, 8, v184
	v_ashrrev_i32_e32 v191, 31, v190
	v_mov_b64_e32 v[184:185], s[42:43]
	v_mad_i64_i32 v[192:193], s[40:41], v200, s88, v[184:185]
	s_andn2_b64 vcc, exec, s[10:11]
	v_pk_fma_f32 v[188:189], v[72:73], v[156:157], v[76:77] op_sel:[0,1,0]
	v_pk_fma_f32 v[210:211], v[74:75], v[156:157], v[78:79] op_sel:[0,1,0]
	v_pk_fma_f32 v[212:213], v[52:53], v[156:157], v[56:57] op_sel:[0,1,0]
	v_pk_fma_f32 v[214:215], v[54:55], v[156:157], v[58:59] op_sel:[0,1,0]
	v_pk_fma_f32 v[216:217], v[202:203], v[156:157], v[206:207] op_sel:[0,1,0]
	v_pk_fma_f32 v[218:219], v[204:205], v[156:157], v[208:209] op_sel:[0,1,0]
	v_pk_fma_f32 v[220:221], v[160:161], v[156:157], v[164:165] op_sel:[0,1,0]
	v_pk_fma_f32 v[222:223], v[162:163], v[156:157], v[166:167] op_sel:[0,1,0]
	v_pk_fma_f32 v[188:189], v[152:153], v[156:157], v[188:189] op_sel_hi:[1,0,1]
	v_pk_fma_f32 v[210:211], v[154:155], v[156:157], v[210:211] op_sel_hi:[1,0,1]
	v_pk_fma_f32 v[212:213], v[144:145], v[156:157], v[212:213] op_sel_hi:[1,0,1]
	v_pk_fma_f32 v[214:215], v[146:147], v[156:157], v[214:215] op_sel_hi:[1,0,1]
	v_pk_fma_f32 v[216:217], v[148:149], v[156:157], v[216:217] op_sel_hi:[1,0,1]
	v_pk_fma_f32 v[218:219], v[150:151], v[156:157], v[218:219] op_sel_hi:[1,0,1]
	v_pk_fma_f32 v[220:221], v[140:141], v[156:157], v[220:221] op_sel_hi:[1,0,1]
	v_pk_fma_f32 v[222:223], v[142:143], v[156:157], v[222:223] op_sel_hi:[1,0,1]
	v_pk_mul_f32 v[224:225], v[188:189], v[186:187] op_sel_hi:[1,0]
	v_pk_mul_f32 v[226:227], v[210:211], v[186:187] op_sel_hi:[1,0]
	v_pk_mul_f32 v[228:229], v[212:213], v[186:187] op_sel_hi:[1,0]
	v_pk_mul_f32 v[230:231], v[214:215], v[186:187] op_sel_hi:[1,0]
	v_exp_f32_e32 v224, v224
	v_exp_f32_e32 v225, v225
	v_exp_f32_e32 v226, v226
	v_exp_f32_e32 v227, v227
	v_exp_f32_e32 v228, v228
	v_exp_f32_e32 v229, v229
	v_exp_f32_e32 v230, v230
	v_exp_f32_e32 v231, v231
	v_pk_add_f32 v[224:225], v[224:225], v[186:187] op_sel:[0,1] op_sel_hi:[1,1]
	v_pk_add_f32 v[226:227], v[226:227], v[186:187] op_sel:[0,1] op_sel_hi:[1,1]
	v_pk_add_f32 v[228:229], v[228:229], v[186:187] op_sel:[0,1] op_sel_hi:[1,1]
	v_pk_add_f32 v[230:231], v[230:231], v[186:187] op_sel:[0,1] op_sel_hi:[1,1]
	v_rcp_f32_e32 v224, v224
	v_rcp_f32_e32 v225, v225
	v_rcp_f32_e32 v226, v226
	v_rcp_f32_e32 v227, v227
	v_rcp_f32_e32 v228, v228
	v_rcp_f32_e32 v229, v229
	v_rcp_f32_e32 v230, v230
	v_rcp_f32_e32 v231, v231
	v_pk_mul_f32 v[224:225], v[188:189], v[224:225]
	v_pk_mul_f32 v[226:227], v[210:211], v[226:227]
	v_pk_mul_f32 v[228:229], v[212:213], v[228:229]
	v_pk_mul_f32 v[230:231], v[214:215], v[230:231]
	v_pk_mul_f32 v[216:217], v[216:217], v[224:225]
	v_pk_mul_f32 v[218:219], v[218:219], v[226:227]
	v_pk_mul_f32 v[220:221], v[220:221], v[228:229]
	v_pk_mul_f32 v[222:223], v[222:223], v[230:231]
	v_cvt_pk_bf16_f32 v232, v216, v217
	v_cvt_pk_bf16_f32 v233, v218, v219
	v_cvt_pk_bf16_f32 v234, v220, v221
	v_cvt_pk_bf16_f32 v235, v222, v223
	v_lshlrev_b64 v[142:143], 1, v[190:191]
	v_lshl_add_u64 v[146:147], v[192:193], 0, v[142:143]
	global_store_dwordx4 v[146:147], v[232:235], off
	v_add_u32_e32 v146, 16, v200
	v_mad_i64_i32 v[146:147], s[40:41], v146, s88, v[184:185]
	v_pk_fma_f32 v[188:189], v[72:73], v[158:159], v[76:77] op_sel:[0,1,0]
	v_pk_fma_f32 v[210:211], v[74:75], v[158:159], v[78:79] op_sel:[0,1,0]
	v_pk_fma_f32 v[212:213], v[52:53], v[158:159], v[56:57] op_sel:[0,1,0]
	v_pk_fma_f32 v[214:215], v[54:55], v[158:159], v[58:59] op_sel:[0,1,0]
	v_pk_fma_f32 v[216:217], v[202:203], v[158:159], v[206:207] op_sel:[0,1,0]
	v_pk_fma_f32 v[218:219], v[204:205], v[158:159], v[208:209] op_sel:[0,1,0]
	v_pk_fma_f32 v[220:221], v[160:161], v[158:159], v[164:165] op_sel:[0,1,0]
	v_pk_fma_f32 v[222:223], v[162:163], v[158:159], v[166:167] op_sel:[0,1,0]
	v_pk_fma_f32 v[188:189], v[132:133], v[158:159], v[188:189] op_sel_hi:[1,0,1]
	v_pk_fma_f32 v[210:211], v[134:135], v[158:159], v[210:211] op_sel_hi:[1,0,1]
	v_pk_fma_f32 v[212:213], v[124:125], v[158:159], v[212:213] op_sel_hi:[1,0,1]
	v_pk_fma_f32 v[214:215], v[126:127], v[158:159], v[214:215] op_sel_hi:[1,0,1]
	v_pk_fma_f32 v[216:217], v[128:129], v[158:159], v[216:217] op_sel_hi:[1,0,1]
	v_pk_fma_f32 v[218:219], v[130:131], v[158:159], v[218:219] op_sel_hi:[1,0,1]
	v_pk_fma_f32 v[220:221], v[120:121], v[158:159], v[220:221] op_sel_hi:[1,0,1]
	v_pk_fma_f32 v[222:223], v[122:123], v[158:159], v[222:223] op_sel_hi:[1,0,1]
	v_pk_mul_f32 v[224:225], v[188:189], v[186:187] op_sel_hi:[1,0]
	v_pk_mul_f32 v[226:227], v[210:211], v[186:187] op_sel_hi:[1,0]
	v_pk_mul_f32 v[228:229], v[212:213], v[186:187] op_sel_hi:[1,0]
	v_pk_mul_f32 v[230:231], v[214:215], v[186:187] op_sel_hi:[1,0]
	v_exp_f32_e32 v224, v224
	v_exp_f32_e32 v225, v225
	v_exp_f32_e32 v226, v226
	v_exp_f32_e32 v227, v227
	v_exp_f32_e32 v228, v228
	v_exp_f32_e32 v229, v229
	v_exp_f32_e32 v230, v230
	v_exp_f32_e32 v231, v231
	v_pk_add_f32 v[224:225], v[224:225], v[186:187] op_sel:[0,1] op_sel_hi:[1,1]
	v_pk_add_f32 v[226:227], v[226:227], v[186:187] op_sel:[0,1] op_sel_hi:[1,1]
	v_pk_add_f32 v[228:229], v[228:229], v[186:187] op_sel:[0,1] op_sel_hi:[1,1]
	v_pk_add_f32 v[230:231], v[230:231], v[186:187] op_sel:[0,1] op_sel_hi:[1,1]
	v_rcp_f32_e32 v224, v224
	v_rcp_f32_e32 v225, v225
	v_rcp_f32_e32 v226, v226
	v_rcp_f32_e32 v227, v227
	v_rcp_f32_e32 v228, v228
	v_rcp_f32_e32 v229, v229
	v_rcp_f32_e32 v230, v230
	v_rcp_f32_e32 v231, v231
	v_pk_mul_f32 v[224:225], v[188:189], v[224:225]
	v_pk_mul_f32 v[226:227], v[210:211], v[226:227]
	v_pk_mul_f32 v[228:229], v[212:213], v[228:229]
	v_pk_mul_f32 v[230:231], v[214:215], v[230:231]
	v_pk_mul_f32 v[216:217], v[216:217], v[224:225]
	v_pk_mul_f32 v[218:219], v[218:219], v[226:227]
	v_pk_mul_f32 v[220:221], v[220:221], v[228:229]
	v_pk_mul_f32 v[222:223], v[222:223], v[230:231]
	v_cvt_pk_bf16_f32 v236, v216, v217
	v_cvt_pk_bf16_f32 v237, v218, v219
	v_cvt_pk_bf16_f32 v238, v220, v221
	v_cvt_pk_bf16_f32 v239, v222, v223
	v_lshl_add_u64 v[124:125], v[146:147], 0, v[142:143]
	global_store_dwordx4 v[124:125], v[236:239], off
	v_add_u32_e32 v120, 32, v200
	v_mad_i64_i32 v[120:121], s[40:41], v120, s88, v[184:185]
	v_pk_fma_f32 v[188:189], v[72:73], v[136:137], v[76:77] op_sel:[0,1,0]
	v_pk_fma_f32 v[210:211], v[74:75], v[136:137], v[78:79] op_sel:[0,1,0]
	v_pk_fma_f32 v[212:213], v[52:53], v[136:137], v[56:57] op_sel:[0,1,0]
	v_pk_fma_f32 v[214:215], v[54:55], v[136:137], v[58:59] op_sel:[0,1,0]
	v_pk_fma_f32 v[216:217], v[202:203], v[136:137], v[206:207] op_sel:[0,1,0]
	v_pk_fma_f32 v[218:219], v[204:205], v[136:137], v[208:209] op_sel:[0,1,0]
	v_pk_fma_f32 v[220:221], v[160:161], v[136:137], v[164:165] op_sel:[0,1,0]
	v_pk_fma_f32 v[222:223], v[162:163], v[136:137], v[166:167] op_sel:[0,1,0]
	v_pk_fma_f32 v[188:189], v[116:117], v[136:137], v[188:189] op_sel_hi:[1,0,1]
	v_pk_fma_f32 v[210:211], v[118:119], v[136:137], v[210:211] op_sel_hi:[1,0,1]
	v_pk_fma_f32 v[212:213], v[108:109], v[136:137], v[212:213] op_sel_hi:[1,0,1]
	v_pk_fma_f32 v[214:215], v[110:111], v[136:137], v[214:215] op_sel_hi:[1,0,1]
	v_pk_fma_f32 v[216:217], v[112:113], v[136:137], v[216:217] op_sel_hi:[1,0,1]
	v_pk_fma_f32 v[218:219], v[114:115], v[136:137], v[218:219] op_sel_hi:[1,0,1]
	v_pk_fma_f32 v[220:221], v[104:105], v[136:137], v[220:221] op_sel_hi:[1,0,1]
	v_pk_fma_f32 v[222:223], v[106:107], v[136:137], v[222:223] op_sel_hi:[1,0,1]
	v_pk_mul_f32 v[224:225], v[188:189], v[186:187] op_sel_hi:[1,0]
	v_pk_mul_f32 v[226:227], v[210:211], v[186:187] op_sel_hi:[1,0]
	v_pk_mul_f32 v[228:229], v[212:213], v[186:187] op_sel_hi:[1,0]
	v_pk_mul_f32 v[230:231], v[214:215], v[186:187] op_sel_hi:[1,0]
	v_exp_f32_e32 v224, v224
	v_exp_f32_e32 v225, v225
	v_exp_f32_e32 v226, v226
	v_exp_f32_e32 v227, v227
	v_exp_f32_e32 v228, v228
	v_exp_f32_e32 v229, v229
	v_exp_f32_e32 v230, v230
	v_exp_f32_e32 v231, v231
	v_pk_add_f32 v[224:225], v[224:225], v[186:187] op_sel:[0,1] op_sel_hi:[1,1]
	v_pk_add_f32 v[226:227], v[226:227], v[186:187] op_sel:[0,1] op_sel_hi:[1,1]
	v_pk_add_f32 v[228:229], v[228:229], v[186:187] op_sel:[0,1] op_sel_hi:[1,1]
	v_pk_add_f32 v[230:231], v[230:231], v[186:187] op_sel:[0,1] op_sel_hi:[1,1]
	v_rcp_f32_e32 v224, v224
	v_rcp_f32_e32 v225, v225
	v_rcp_f32_e32 v226, v226
	v_rcp_f32_e32 v227, v227
	v_rcp_f32_e32 v228, v228
	v_rcp_f32_e32 v229, v229
	v_rcp_f32_e32 v230, v230
	v_rcp_f32_e32 v231, v231
	v_pk_mul_f32 v[224:225], v[188:189], v[224:225]
	v_pk_mul_f32 v[226:227], v[210:211], v[226:227]
	v_pk_mul_f32 v[228:229], v[212:213], v[228:229]
	v_pk_mul_f32 v[230:231], v[214:215], v[230:231]
	v_pk_mul_f32 v[216:217], v[216:217], v[224:225]
	v_pk_mul_f32 v[218:219], v[218:219], v[226:227]
	v_pk_mul_f32 v[220:221], v[220:221], v[228:229]
	v_pk_mul_f32 v[222:223], v[222:223], v[230:231]
	v_cvt_pk_bf16_f32 v240, v216, v217
	v_cvt_pk_bf16_f32 v241, v218, v219
	v_cvt_pk_bf16_f32 v242, v220, v221
	v_cvt_pk_bf16_f32 v243, v222, v223
	v_lshl_add_u64 v[108:109], v[120:121], 0, v[142:143]
	global_store_dwordx4 v[108:109], v[240:243], off
	v_add_u32_e32 v104, 48, v200
	v_mad_i64_i32 v[104:105], s[40:41], v104, s88, v[184:185]
	v_pk_fma_f32 v[188:189], v[72:73], v[138:139], v[76:77] op_sel:[0,1,0]
	v_pk_fma_f32 v[210:211], v[74:75], v[138:139], v[78:79] op_sel:[0,1,0]
	v_pk_fma_f32 v[212:213], v[52:53], v[138:139], v[56:57] op_sel:[0,1,0]
	v_pk_fma_f32 v[214:215], v[54:55], v[138:139], v[58:59] op_sel:[0,1,0]
	v_pk_fma_f32 v[216:217], v[202:203], v[138:139], v[206:207] op_sel:[0,1,0]
	v_pk_fma_f32 v[218:219], v[204:205], v[138:139], v[208:209] op_sel:[0,1,0]
	v_pk_fma_f32 v[220:221], v[160:161], v[138:139], v[164:165] op_sel:[0,1,0]
	v_pk_fma_f32 v[222:223], v[162:163], v[138:139], v[166:167] op_sel:[0,1,0]
	v_pk_fma_f32 v[188:189], v[96:97], v[138:139], v[188:189] op_sel_hi:[1,0,1]
	v_pk_fma_f32 v[210:211], v[98:99], v[138:139], v[210:211] op_sel_hi:[1,0,1]
	v_pk_fma_f32 v[212:213], v[88:89], v[138:139], v[212:213] op_sel_hi:[1,0,1]
	v_pk_fma_f32 v[214:215], v[90:91], v[138:139], v[214:215] op_sel_hi:[1,0,1]
	v_pk_fma_f32 v[216:217], v[92:93], v[138:139], v[216:217] op_sel_hi:[1,0,1]
	v_pk_fma_f32 v[218:219], v[94:95], v[138:139], v[218:219] op_sel_hi:[1,0,1]
	v_pk_fma_f32 v[220:221], v[84:85], v[138:139], v[220:221] op_sel_hi:[1,0,1]
	v_pk_fma_f32 v[222:223], v[86:87], v[138:139], v[222:223] op_sel_hi:[1,0,1]
	v_pk_mul_f32 v[224:225], v[188:189], v[186:187] op_sel_hi:[1,0]
	v_pk_mul_f32 v[226:227], v[210:211], v[186:187] op_sel_hi:[1,0]
	v_pk_mul_f32 v[228:229], v[212:213], v[186:187] op_sel_hi:[1,0]
	v_pk_mul_f32 v[230:231], v[214:215], v[186:187] op_sel_hi:[1,0]
	v_exp_f32_e32 v224, v224
	v_exp_f32_e32 v225, v225
	v_exp_f32_e32 v226, v226
	v_exp_f32_e32 v227, v227
	v_exp_f32_e32 v228, v228
	v_exp_f32_e32 v229, v229
	v_exp_f32_e32 v230, v230
	v_exp_f32_e32 v231, v231
	v_pk_add_f32 v[224:225], v[224:225], v[186:187] op_sel:[0,1] op_sel_hi:[1,1]
	v_pk_add_f32 v[226:227], v[226:227], v[186:187] op_sel:[0,1] op_sel_hi:[1,1]
	v_pk_add_f32 v[228:229], v[228:229], v[186:187] op_sel:[0,1] op_sel_hi:[1,1]
	v_pk_add_f32 v[230:231], v[230:231], v[186:187] op_sel:[0,1] op_sel_hi:[1,1]
	v_rcp_f32_e32 v224, v224
	v_rcp_f32_e32 v225, v225
	v_rcp_f32_e32 v226, v226
	v_rcp_f32_e32 v227, v227
	v_rcp_f32_e32 v228, v228
	v_rcp_f32_e32 v229, v229
	v_rcp_f32_e32 v230, v230
	v_rcp_f32_e32 v231, v231
	v_pk_mul_f32 v[224:225], v[188:189], v[224:225]
	v_pk_mul_f32 v[226:227], v[210:211], v[226:227]
	v_pk_mul_f32 v[228:229], v[212:213], v[228:229]
	v_pk_mul_f32 v[230:231], v[214:215], v[230:231]
	v_pk_mul_f32 v[216:217], v[216:217], v[224:225]
	v_pk_mul_f32 v[218:219], v[218:219], v[226:227]
	v_pk_mul_f32 v[220:221], v[220:221], v[228:229]
	v_pk_mul_f32 v[222:223], v[222:223], v[230:231]
	v_cvt_pk_bf16_f32 v244, v216, v217
	v_cvt_pk_bf16_f32 v245, v218, v219
	v_cvt_pk_bf16_f32 v246, v220, v221
	v_cvt_pk_bf16_f32 v247, v222, v223
	v_lshl_add_u64 v[88:89], v[104:105], 0, v[142:143]
	global_store_dwordx4 v[88:89], v[244:247], off
	v_add_u32_e32 v84, 0x80, v200
	v_mad_i64_i32 v[84:85], s[40:41], v84, s88, v[184:185]
	v_pk_fma_f32 v[188:189], v[72:73], v[100:101], v[76:77] op_sel:[0,1,0]
	v_pk_fma_f32 v[210:211], v[74:75], v[100:101], v[78:79] op_sel:[0,1,0]
	v_pk_fma_f32 v[212:213], v[52:53], v[100:101], v[56:57] op_sel:[0,1,0]
	v_pk_fma_f32 v[214:215], v[54:55], v[100:101], v[58:59] op_sel:[0,1,0]
	v_pk_fma_f32 v[216:217], v[202:203], v[100:101], v[206:207] op_sel:[0,1,0]
	v_pk_fma_f32 v[218:219], v[204:205], v[100:101], v[208:209] op_sel:[0,1,0]
	v_pk_fma_f32 v[220:221], v[160:161], v[100:101], v[164:165] op_sel:[0,1,0]
	v_pk_fma_f32 v[222:223], v[162:163], v[100:101], v[166:167] op_sel:[0,1,0]
	v_pk_fma_f32 v[188:189], v[80:81], v[100:101], v[188:189] op_sel_hi:[1,0,1]
	v_pk_fma_f32 v[210:211], v[82:83], v[100:101], v[210:211] op_sel_hi:[1,0,1]
	v_pk_fma_f32 v[212:213], v[60:61], v[100:101], v[212:213] op_sel_hi:[1,0,1]
	v_pk_fma_f32 v[214:215], v[62:63], v[100:101], v[214:215] op_sel_hi:[1,0,1]
	v_pk_fma_f32 v[216:217], v[68:69], v[100:101], v[216:217] op_sel_hi:[1,0,1]
	v_pk_fma_f32 v[218:219], v[70:71], v[100:101], v[218:219] op_sel_hi:[1,0,1]
	v_pk_fma_f32 v[220:221], v[48:49], v[100:101], v[220:221] op_sel_hi:[1,0,1]
	v_pk_fma_f32 v[222:223], v[50:51], v[100:101], v[222:223] op_sel_hi:[1,0,1]
	v_pk_mul_f32 v[224:225], v[188:189], v[186:187] op_sel_hi:[1,0]
	v_pk_mul_f32 v[226:227], v[210:211], v[186:187] op_sel_hi:[1,0]
	v_pk_mul_f32 v[228:229], v[212:213], v[186:187] op_sel_hi:[1,0]
	v_pk_mul_f32 v[230:231], v[214:215], v[186:187] op_sel_hi:[1,0]
	v_exp_f32_e32 v224, v224
	v_exp_f32_e32 v225, v225
	v_exp_f32_e32 v226, v226
	v_exp_f32_e32 v227, v227
	v_exp_f32_e32 v228, v228
	v_exp_f32_e32 v229, v229
	v_exp_f32_e32 v230, v230
	v_exp_f32_e32 v231, v231
	v_pk_add_f32 v[224:225], v[224:225], v[186:187] op_sel:[0,1] op_sel_hi:[1,1]
	v_pk_add_f32 v[226:227], v[226:227], v[186:187] op_sel:[0,1] op_sel_hi:[1,1]
	v_pk_add_f32 v[228:229], v[228:229], v[186:187] op_sel:[0,1] op_sel_hi:[1,1]
	v_pk_add_f32 v[230:231], v[230:231], v[186:187] op_sel:[0,1] op_sel_hi:[1,1]
	v_rcp_f32_e32 v224, v224
	v_rcp_f32_e32 v225, v225
	v_rcp_f32_e32 v226, v226
	v_rcp_f32_e32 v227, v227
	v_rcp_f32_e32 v228, v228
	v_rcp_f32_e32 v229, v229
	v_rcp_f32_e32 v230, v230
	v_rcp_f32_e32 v231, v231
	v_pk_mul_f32 v[224:225], v[188:189], v[224:225]
	v_pk_mul_f32 v[226:227], v[210:211], v[226:227]
	v_pk_mul_f32 v[228:229], v[212:213], v[228:229]
	v_pk_mul_f32 v[230:231], v[214:215], v[230:231]
	v_pk_mul_f32 v[216:217], v[216:217], v[224:225]
	v_pk_mul_f32 v[218:219], v[218:219], v[226:227]
	v_pk_mul_f32 v[220:221], v[220:221], v[228:229]
	v_pk_mul_f32 v[222:223], v[222:223], v[230:231]
	v_cvt_pk_bf16_f32 v248, v216, v217
	v_cvt_pk_bf16_f32 v249, v218, v219
	v_cvt_pk_bf16_f32 v250, v220, v221
	v_cvt_pk_bf16_f32 v251, v222, v223
	v_lshl_add_u64 v[60:61], v[84:85], 0, v[142:143]
	global_store_dwordx4 v[60:61], v[248:251], off
	v_add_u32_e32 v48, 0x90, v200
	v_mad_i64_i32 v[48:49], s[40:41], v48, s88, v[184:185]
	v_pk_fma_f32 v[188:189], v[72:73], v[102:103], v[76:77] op_sel:[0,1,0]
	v_pk_fma_f32 v[210:211], v[74:75], v[102:103], v[78:79] op_sel:[0,1,0]
	v_pk_fma_f32 v[212:213], v[52:53], v[102:103], v[56:57] op_sel:[0,1,0]
	v_pk_fma_f32 v[214:215], v[54:55], v[102:103], v[58:59] op_sel:[0,1,0]
	v_pk_fma_f32 v[216:217], v[202:203], v[102:103], v[206:207] op_sel:[0,1,0]
	v_pk_fma_f32 v[218:219], v[204:205], v[102:103], v[208:209] op_sel:[0,1,0]
	v_pk_fma_f32 v[220:221], v[160:161], v[102:103], v[164:165] op_sel:[0,1,0]
	v_pk_fma_f32 v[222:223], v[162:163], v[102:103], v[166:167] op_sel:[0,1,0]
	v_pk_fma_f32 v[188:189], v[44:45], v[102:103], v[188:189] op_sel_hi:[1,0,1]
	v_pk_fma_f32 v[210:211], v[46:47], v[102:103], v[210:211] op_sel_hi:[1,0,1]
	v_pk_fma_f32 v[212:213], v[36:37], v[102:103], v[212:213] op_sel_hi:[1,0,1]
	v_pk_fma_f32 v[214:215], v[38:39], v[102:103], v[214:215] op_sel_hi:[1,0,1]
	v_pk_fma_f32 v[216:217], v[40:41], v[102:103], v[216:217] op_sel_hi:[1,0,1]
	v_pk_fma_f32 v[218:219], v[42:43], v[102:103], v[218:219] op_sel_hi:[1,0,1]
	v_pk_fma_f32 v[220:221], v[32:33], v[102:103], v[220:221] op_sel_hi:[1,0,1]
	v_pk_fma_f32 v[222:223], v[34:35], v[102:103], v[222:223] op_sel_hi:[1,0,1]
	v_pk_mul_f32 v[224:225], v[188:189], v[186:187] op_sel_hi:[1,0]
	v_pk_mul_f32 v[226:227], v[210:211], v[186:187] op_sel_hi:[1,0]
	v_pk_mul_f32 v[228:229], v[212:213], v[186:187] op_sel_hi:[1,0]
	v_pk_mul_f32 v[230:231], v[214:215], v[186:187] op_sel_hi:[1,0]
	v_exp_f32_e32 v224, v224
	v_exp_f32_e32 v225, v225
	v_exp_f32_e32 v226, v226
	v_exp_f32_e32 v227, v227
	v_exp_f32_e32 v228, v228
	v_exp_f32_e32 v229, v229
	v_exp_f32_e32 v230, v230
	v_exp_f32_e32 v231, v231
	v_pk_add_f32 v[224:225], v[224:225], v[186:187] op_sel:[0,1] op_sel_hi:[1,1]
	v_pk_add_f32 v[226:227], v[226:227], v[186:187] op_sel:[0,1] op_sel_hi:[1,1]
	v_pk_add_f32 v[228:229], v[228:229], v[186:187] op_sel:[0,1] op_sel_hi:[1,1]
	v_pk_add_f32 v[230:231], v[230:231], v[186:187] op_sel:[0,1] op_sel_hi:[1,1]
	v_rcp_f32_e32 v224, v224
	v_rcp_f32_e32 v225, v225
	v_rcp_f32_e32 v226, v226
	v_rcp_f32_e32 v227, v227
	v_rcp_f32_e32 v228, v228
	v_rcp_f32_e32 v229, v229
	v_rcp_f32_e32 v230, v230
	v_rcp_f32_e32 v231, v231
	v_pk_mul_f32 v[224:225], v[188:189], v[224:225]
	v_pk_mul_f32 v[226:227], v[210:211], v[226:227]
	v_pk_mul_f32 v[228:229], v[212:213], v[228:229]
	v_pk_mul_f32 v[230:231], v[214:215], v[230:231]
	v_pk_mul_f32 v[216:217], v[216:217], v[224:225]
	v_pk_mul_f32 v[218:219], v[218:219], v[226:227]
	v_pk_mul_f32 v[220:221], v[220:221], v[228:229]
	v_pk_mul_f32 v[222:223], v[222:223], v[230:231]
	v_cvt_pk_bf16_f32 v232, v216, v217
	v_cvt_pk_bf16_f32 v233, v218, v219
	v_cvt_pk_bf16_f32 v234, v220, v221
	v_cvt_pk_bf16_f32 v235, v222, v223
	v_lshl_add_u64 v[36:37], v[48:49], 0, v[142:143]
	global_store_dwordx4 v[36:37], v[232:235], off
	v_add_u32_e32 v32, 0xa0, v200
	v_mad_i64_i32 v[32:33], s[40:41], v32, s88, v[184:185]
	v_pk_fma_f32 v[188:189], v[72:73], v[64:65], v[76:77] op_sel:[0,1,0]
	v_pk_fma_f32 v[210:211], v[74:75], v[64:65], v[78:79] op_sel:[0,1,0]
	v_pk_fma_f32 v[212:213], v[52:53], v[64:65], v[56:57] op_sel:[0,1,0]
	v_pk_fma_f32 v[214:215], v[54:55], v[64:65], v[58:59] op_sel:[0,1,0]
	v_pk_fma_f32 v[216:217], v[202:203], v[64:65], v[206:207] op_sel:[0,1,0]
	v_pk_fma_f32 v[218:219], v[204:205], v[64:65], v[208:209] op_sel:[0,1,0]
	v_pk_fma_f32 v[220:221], v[160:161], v[64:65], v[164:165] op_sel:[0,1,0]
	v_pk_fma_f32 v[222:223], v[162:163], v[64:65], v[166:167] op_sel:[0,1,0]
	v_pk_fma_f32 v[188:189], v[28:29], v[64:65], v[188:189] op_sel_hi:[1,0,1]
	v_pk_fma_f32 v[210:211], v[30:31], v[64:65], v[210:211] op_sel_hi:[1,0,1]
	v_pk_fma_f32 v[212:213], v[20:21], v[64:65], v[212:213] op_sel_hi:[1,0,1]
	v_pk_fma_f32 v[214:215], v[22:23], v[64:65], v[214:215] op_sel_hi:[1,0,1]
	v_pk_fma_f32 v[216:217], v[24:25], v[64:65], v[216:217] op_sel_hi:[1,0,1]
	v_pk_fma_f32 v[218:219], v[26:27], v[64:65], v[218:219] op_sel_hi:[1,0,1]
	v_pk_fma_f32 v[220:221], v[16:17], v[64:65], v[220:221] op_sel_hi:[1,0,1]
	v_pk_fma_f32 v[222:223], v[18:19], v[64:65], v[222:223] op_sel_hi:[1,0,1]
	v_pk_mul_f32 v[224:225], v[188:189], v[186:187] op_sel_hi:[1,0]
	v_pk_mul_f32 v[226:227], v[210:211], v[186:187] op_sel_hi:[1,0]
	v_pk_mul_f32 v[228:229], v[212:213], v[186:187] op_sel_hi:[1,0]
	v_pk_mul_f32 v[230:231], v[214:215], v[186:187] op_sel_hi:[1,0]
	v_exp_f32_e32 v224, v224
	v_exp_f32_e32 v225, v225
	v_exp_f32_e32 v226, v226
	v_exp_f32_e32 v227, v227
	v_exp_f32_e32 v228, v228
	v_exp_f32_e32 v229, v229
	v_exp_f32_e32 v230, v230
	v_exp_f32_e32 v231, v231
	v_pk_add_f32 v[224:225], v[224:225], v[186:187] op_sel:[0,1] op_sel_hi:[1,1]
	v_pk_add_f32 v[226:227], v[226:227], v[186:187] op_sel:[0,1] op_sel_hi:[1,1]
	v_pk_add_f32 v[228:229], v[228:229], v[186:187] op_sel:[0,1] op_sel_hi:[1,1]
	v_pk_add_f32 v[230:231], v[230:231], v[186:187] op_sel:[0,1] op_sel_hi:[1,1]
	v_rcp_f32_e32 v224, v224
	v_rcp_f32_e32 v225, v225
	v_rcp_f32_e32 v226, v226
	v_rcp_f32_e32 v227, v227
	v_rcp_f32_e32 v228, v228
	v_rcp_f32_e32 v229, v229
	v_rcp_f32_e32 v230, v230
	v_rcp_f32_e32 v231, v231
	v_pk_mul_f32 v[224:225], v[188:189], v[224:225]
	v_pk_mul_f32 v[226:227], v[210:211], v[226:227]
	v_pk_mul_f32 v[228:229], v[212:213], v[228:229]
	v_pk_mul_f32 v[230:231], v[214:215], v[230:231]
	v_pk_mul_f32 v[216:217], v[216:217], v[224:225]
	v_pk_mul_f32 v[218:219], v[218:219], v[226:227]
	v_pk_mul_f32 v[220:221], v[220:221], v[228:229]
	v_pk_mul_f32 v[222:223], v[222:223], v[230:231]
	v_cvt_pk_bf16_f32 v236, v216, v217
	v_cvt_pk_bf16_f32 v237, v218, v219
	v_cvt_pk_bf16_f32 v238, v220, v221
	v_cvt_pk_bf16_f32 v239, v222, v223
	v_lshl_add_u64 v[20:21], v[32:33], 0, v[142:143]
	global_store_dwordx4 v[20:21], v[236:239], off
	v_add_u32_e32 v16, 0xb0, v200
	v_mad_i64_i32 v[16:17], s[40:41], v16, s88, v[184:185]
	s_nop 1
	s_mov_b64 s[40:41], -1
	v_pk_fma_f32 v[188:189], v[72:73], v[66:67], v[76:77] op_sel:[0,1,0]
	v_pk_fma_f32 v[210:211], v[74:75], v[66:67], v[78:79] op_sel:[0,1,0]
	v_pk_fma_f32 v[212:213], v[52:53], v[66:67], v[56:57] op_sel:[0,1,0]
	v_pk_fma_f32 v[214:215], v[54:55], v[66:67], v[58:59] op_sel:[0,1,0]
	v_pk_fma_f32 v[216:217], v[202:203], v[66:67], v[206:207] op_sel:[0,1,0]
	v_pk_fma_f32 v[218:219], v[204:205], v[66:67], v[208:209] op_sel:[0,1,0]
	v_pk_fma_f32 v[220:221], v[160:161], v[66:67], v[164:165] op_sel:[0,1,0]
	v_pk_fma_f32 v[222:223], v[162:163], v[66:67], v[166:167] op_sel:[0,1,0]
	v_pk_fma_f32 v[188:189], v[12:13], v[66:67], v[188:189] op_sel_hi:[1,0,1]
	v_pk_fma_f32 v[210:211], v[14:15], v[66:67], v[210:211] op_sel_hi:[1,0,1]
	v_pk_fma_f32 v[212:213], v[4:5], v[66:67], v[212:213] op_sel_hi:[1,0,1]
	v_pk_fma_f32 v[214:215], v[6:7], v[66:67], v[214:215] op_sel_hi:[1,0,1]
	v_pk_fma_f32 v[216:217], v[8:9], v[66:67], v[216:217] op_sel_hi:[1,0,1]
	v_pk_fma_f32 v[218:219], v[10:11], v[66:67], v[218:219] op_sel_hi:[1,0,1]
	v_pk_fma_f32 v[220:221], v[0:1], v[66:67], v[220:221] op_sel_hi:[1,0,1]
	v_pk_fma_f32 v[222:223], v[2:3], v[66:67], v[222:223] op_sel_hi:[1,0,1]
	v_pk_mul_f32 v[224:225], v[188:189], v[186:187] op_sel_hi:[1,0]
	v_pk_mul_f32 v[226:227], v[210:211], v[186:187] op_sel_hi:[1,0]
	v_pk_mul_f32 v[228:229], v[212:213], v[186:187] op_sel_hi:[1,0]
	v_pk_mul_f32 v[230:231], v[214:215], v[186:187] op_sel_hi:[1,0]
	v_exp_f32_e32 v224, v224
	v_exp_f32_e32 v225, v225
	v_exp_f32_e32 v226, v226
	v_exp_f32_e32 v227, v227
	v_exp_f32_e32 v228, v228
	v_exp_f32_e32 v229, v229
	v_exp_f32_e32 v230, v230
	v_exp_f32_e32 v231, v231
	v_pk_add_f32 v[224:225], v[224:225], v[186:187] op_sel:[0,1] op_sel_hi:[1,1]
	v_pk_add_f32 v[226:227], v[226:227], v[186:187] op_sel:[0,1] op_sel_hi:[1,1]
	v_pk_add_f32 v[228:229], v[228:229], v[186:187] op_sel:[0,1] op_sel_hi:[1,1]
	v_pk_add_f32 v[230:231], v[230:231], v[186:187] op_sel:[0,1] op_sel_hi:[1,1]
	v_rcp_f32_e32 v224, v224
	v_rcp_f32_e32 v225, v225
	v_rcp_f32_e32 v226, v226
	v_rcp_f32_e32 v227, v227
	v_rcp_f32_e32 v228, v228
	v_rcp_f32_e32 v229, v229
	v_rcp_f32_e32 v230, v230
	v_rcp_f32_e32 v231, v231
	v_pk_mul_f32 v[224:225], v[188:189], v[224:225]
	v_pk_mul_f32 v[226:227], v[210:211], v[226:227]
	v_pk_mul_f32 v[228:229], v[212:213], v[228:229]
	v_pk_mul_f32 v[230:231], v[214:215], v[230:231]
	v_pk_mul_f32 v[216:217], v[216:217], v[224:225]
	v_pk_mul_f32 v[218:219], v[218:219], v[226:227]
	v_pk_mul_f32 v[220:221], v[220:221], v[228:229]
	v_pk_mul_f32 v[222:223], v[222:223], v[230:231]
	v_cvt_pk_bf16_f32 v240, v216, v217
	v_cvt_pk_bf16_f32 v241, v218, v219
	v_cvt_pk_bf16_f32 v242, v220, v221
	v_cvt_pk_bf16_f32 v243, v222, v223
	v_lshl_add_u64 v[4:5], v[16:17], 0, v[142:143]
	global_store_dwordx4 v[4:5], v[240:243], off
	s_mov_b32 s99, 1
	s_cbranch_vccnz .LBB0_1602
	s_andn2_b64 vcc, exec, s[0:1]
	s_cbranch_vccnz .LBB0_1601
	s_barrier
	s_branch .LBB0_1601

.LBB0_2473:
	v_mov_b32_e32 v186, 0xbfb8aa3b
	v_mov_b32_e32 v187, 1.0
	s_cmp_eq_u32 s40, s66
	s_movk_i32 s15, 0x200
	s_cselect_b32 s15, s15, 0x300
	s_cmp_lg_u32 s40, s65
	v_mov_b32_e32 v64, v194
	v_mov_b32_e32 v65, v195
	s_cselect_b32 s15, s15, 0x100
	s_cmp_lg_u32 s40, s64
	s_cselect_b32 s15, s15, 0
	v_lshl_add_u32 v66, v65, 5, s85
	v_add_u32_e32 v184, s78, v64
	ds_read_b128 v[72:75], v66
	ds_read_b128 v[52:55], v66 offset:16
	ds_read_b128 v[76:79], v66 offset:256
	ds_read_b128 v[56:59], v66 offset:272
	ds_read_b128 v[202:205], v66 offset:128
	ds_read_b128 v[206:209], v66 offset:384
	ds_read_b128 v[160:163], v66 offset:144
	ds_read_b128 v[164:167], v66 offset:400
	s_lshl_b32 s35, s41, 7
	v_add_u32_e32 v64, s15, v184
	s_or_b32 s35, s35, s79
	v_lshl_add_u32 v64, v64, 3, v199
	v_lshl_add_u32 v190, v65, 3, s35
	ds_read2_b64 v[156:159], v64 offset1:16
	ds_read2_b64 v[136:139], v64 offset0:32 offset1:48
	ds_read2_b64 v[100:103], v64 offset0:128 offset1:144
	ds_read2_b64 v[64:67], v64 offset0:160 offset1:176
	s_waitcnt lgkmcnt(0)
	v_lshl_add_u32 v200, s40, 8, v184
	v_ashrrev_i32_e32 v191, 31, v190
	v_mov_b64_e32 v[184:185], s[42:43]
	v_mad_i64_i32 v[192:193], s[40:41], v200, s88, v[184:185]
	s_andn2_b64 vcc, exec, s[10:11]
	v_readlane_b32 s96, v255, 18
	v_readlane_b32 s97, v255, 19
	v_pk_fma_f32 v[188:189], v[72:73], v[156:157], v[76:77] op_sel:[0,1,0]
	v_pk_fma_f32 v[210:211], v[74:75], v[156:157], v[78:79] op_sel:[0,1,0]
	v_pk_fma_f32 v[212:213], v[52:53], v[156:157], v[56:57] op_sel:[0,1,0]
	v_pk_fma_f32 v[214:215], v[54:55], v[156:157], v[58:59] op_sel:[0,1,0]
	v_pk_fma_f32 v[216:217], v[202:203], v[156:157], v[206:207] op_sel:[0,1,0]
	v_pk_fma_f32 v[218:219], v[204:205], v[156:157], v[208:209] op_sel:[0,1,0]
	v_pk_fma_f32 v[220:221], v[160:161], v[156:157], v[164:165] op_sel:[0,1,0]
	v_pk_fma_f32 v[222:223], v[162:163], v[156:157], v[166:167] op_sel:[0,1,0]
	v_pk_fma_f32 v[188:189], v[152:153], v[156:157], v[188:189] op_sel_hi:[1,0,1]
	v_pk_fma_f32 v[210:211], v[154:155], v[156:157], v[210:211] op_sel_hi:[1,0,1]
	v_pk_fma_f32 v[212:213], v[144:145], v[156:157], v[212:213] op_sel_hi:[1,0,1]
	v_pk_fma_f32 v[214:215], v[146:147], v[156:157], v[214:215] op_sel_hi:[1,0,1]
	v_pk_fma_f32 v[216:217], v[148:149], v[156:157], v[216:217] op_sel_hi:[1,0,1]
	v_pk_fma_f32 v[218:219], v[150:151], v[156:157], v[218:219] op_sel_hi:[1,0,1]
	v_pk_fma_f32 v[220:221], v[140:141], v[156:157], v[220:221] op_sel_hi:[1,0,1]
	v_pk_fma_f32 v[222:223], v[142:143], v[156:157], v[222:223] op_sel_hi:[1,0,1]
	v_pk_mul_f32 v[224:225], v[188:189], v[186:187] op_sel_hi:[1,0]
	v_pk_mul_f32 v[226:227], v[210:211], v[186:187] op_sel_hi:[1,0]
	v_pk_mul_f32 v[228:229], v[212:213], v[186:187] op_sel_hi:[1,0]
	v_pk_mul_f32 v[230:231], v[214:215], v[186:187] op_sel_hi:[1,0]
	v_exp_f32_e32 v224, v224
	v_exp_f32_e32 v225, v225
	v_exp_f32_e32 v226, v226
	v_exp_f32_e32 v227, v227
	v_exp_f32_e32 v228, v228
	v_exp_f32_e32 v229, v229
	v_exp_f32_e32 v230, v230
	v_exp_f32_e32 v231, v231
	v_pk_add_f32 v[224:225], v[224:225], v[186:187] op_sel:[0,1] op_sel_hi:[1,1]
	v_pk_add_f32 v[226:227], v[226:227], v[186:187] op_sel:[0,1] op_sel_hi:[1,1]
	v_pk_add_f32 v[228:229], v[228:229], v[186:187] op_sel:[0,1] op_sel_hi:[1,1]
	v_pk_add_f32 v[230:231], v[230:231], v[186:187] op_sel:[0,1] op_sel_hi:[1,1]
	v_rcp_f32_e32 v224, v224
	v_rcp_f32_e32 v225, v225
	v_rcp_f32_e32 v226, v226
	v_rcp_f32_e32 v227, v227
	v_rcp_f32_e32 v228, v228
	v_rcp_f32_e32 v229, v229
	v_rcp_f32_e32 v230, v230
	v_rcp_f32_e32 v231, v231
	v_pk_mul_f32 v[224:225], v[188:189], v[224:225]
	v_pk_mul_f32 v[226:227], v[210:211], v[226:227]
	v_pk_mul_f32 v[228:229], v[212:213], v[228:229]
	v_pk_mul_f32 v[230:231], v[214:215], v[230:231]
	v_pk_mul_f32 v[216:217], v[216:217], v[224:225]
	v_pk_mul_f32 v[218:219], v[218:219], v[226:227]
	v_pk_mul_f32 v[220:221], v[220:221], v[228:229]
	v_pk_mul_f32 v[222:223], v[222:223], v[230:231]
	v_cvt_pk_bf16_f32 v232, v216, v217
	v_cvt_pk_bf16_f32 v233, v218, v219
	v_cvt_pk_bf16_f32 v234, v220, v221
	v_cvt_pk_bf16_f32 v235, v222, v223
	v_lshlrev_b64 v[142:143], 1, v[190:191]
	v_lshl_add_u64 v[146:147], v[192:193], 0, v[142:143]
	global_store_dwordx4 v[146:147], v[232:235], off
	v_add_u32_e32 v146, 16, v200
	v_mad_i64_i32 v[146:147], s[40:41], v146, s88, v[184:185]
	v_pk_fma_f32 v[188:189], v[72:73], v[158:159], v[76:77] op_sel:[0,1,0]
	v_pk_fma_f32 v[210:211], v[74:75], v[158:159], v[78:79] op_sel:[0,1,0]
	v_pk_fma_f32 v[212:213], v[52:53], v[158:159], v[56:57] op_sel:[0,1,0]
	v_pk_fma_f32 v[214:215], v[54:55], v[158:159], v[58:59] op_sel:[0,1,0]
	v_pk_fma_f32 v[216:217], v[202:203], v[158:159], v[206:207] op_sel:[0,1,0]
	v_pk_fma_f32 v[218:219], v[204:205], v[158:159], v[208:209] op_sel:[0,1,0]
	v_pk_fma_f32 v[220:221], v[160:161], v[158:159], v[164:165] op_sel:[0,1,0]
	v_pk_fma_f32 v[222:223], v[162:163], v[158:159], v[166:167] op_sel:[0,1,0]
	v_pk_fma_f32 v[188:189], v[132:133], v[158:159], v[188:189] op_sel_hi:[1,0,1]
	v_pk_fma_f32 v[210:211], v[134:135], v[158:159], v[210:211] op_sel_hi:[1,0,1]
	v_pk_fma_f32 v[212:213], v[124:125], v[158:159], v[212:213] op_sel_hi:[1,0,1]
	v_pk_fma_f32 v[214:215], v[126:127], v[158:159], v[214:215] op_sel_hi:[1,0,1]
	v_pk_fma_f32 v[216:217], v[128:129], v[158:159], v[216:217] op_sel_hi:[1,0,1]
	v_pk_fma_f32 v[218:219], v[130:131], v[158:159], v[218:219] op_sel_hi:[1,0,1]
	v_pk_fma_f32 v[220:221], v[120:121], v[158:159], v[220:221] op_sel_hi:[1,0,1]
	v_pk_fma_f32 v[222:223], v[122:123], v[158:159], v[222:223] op_sel_hi:[1,0,1]
	v_pk_mul_f32 v[224:225], v[188:189], v[186:187] op_sel_hi:[1,0]
	v_pk_mul_f32 v[226:227], v[210:211], v[186:187] op_sel_hi:[1,0]
	v_pk_mul_f32 v[228:229], v[212:213], v[186:187] op_sel_hi:[1,0]
	v_pk_mul_f32 v[230:231], v[214:215], v[186:187] op_sel_hi:[1,0]
	v_exp_f32_e32 v224, v224
	v_exp_f32_e32 v225, v225
	v_exp_f32_e32 v226, v226
	v_exp_f32_e32 v227, v227
	v_exp_f32_e32 v228, v228
	v_exp_f32_e32 v229, v229
	v_exp_f32_e32 v230, v230
	v_exp_f32_e32 v231, v231
	v_pk_add_f32 v[224:225], v[224:225], v[186:187] op_sel:[0,1] op_sel_hi:[1,1]
	v_pk_add_f32 v[226:227], v[226:227], v[186:187] op_sel:[0,1] op_sel_hi:[1,1]
	v_pk_add_f32 v[228:229], v[228:229], v[186:187] op_sel:[0,1] op_sel_hi:[1,1]
	v_pk_add_f32 v[230:231], v[230:231], v[186:187] op_sel:[0,1] op_sel_hi:[1,1]
	v_rcp_f32_e32 v224, v224
	v_rcp_f32_e32 v225, v225
	v_rcp_f32_e32 v226, v226
	v_rcp_f32_e32 v227, v227
	v_rcp_f32_e32 v228, v228
	v_rcp_f32_e32 v229, v229
	v_rcp_f32_e32 v230, v230
	v_rcp_f32_e32 v231, v231
	v_pk_mul_f32 v[224:225], v[188:189], v[224:225]
	v_pk_mul_f32 v[226:227], v[210:211], v[226:227]
	v_pk_mul_f32 v[228:229], v[212:213], v[228:229]
	v_pk_mul_f32 v[230:231], v[214:215], v[230:231]
	v_pk_mul_f32 v[216:217], v[216:217], v[224:225]
	v_pk_mul_f32 v[218:219], v[218:219], v[226:227]
	v_pk_mul_f32 v[220:221], v[220:221], v[228:229]
	v_pk_mul_f32 v[222:223], v[222:223], v[230:231]
	v_cvt_pk_bf16_f32 v236, v216, v217
	v_cvt_pk_bf16_f32 v237, v218, v219
	v_cvt_pk_bf16_f32 v238, v220, v221
	v_cvt_pk_bf16_f32 v239, v222, v223
	v_lshl_add_u64 v[124:125], v[146:147], 0, v[142:143]
	global_store_dwordx4 v[124:125], v[236:239], off
	v_add_u32_e32 v120, 32, v200
	v_mad_i64_i32 v[120:121], s[40:41], v120, s88, v[184:185]
	v_pk_fma_f32 v[188:189], v[72:73], v[136:137], v[76:77] op_sel:[0,1,0]
	v_pk_fma_f32 v[210:211], v[74:75], v[136:137], v[78:79] op_sel:[0,1,0]
	v_pk_fma_f32 v[212:213], v[52:53], v[136:137], v[56:57] op_sel:[0,1,0]
	v_pk_fma_f32 v[214:215], v[54:55], v[136:137], v[58:59] op_sel:[0,1,0]
	v_pk_fma_f32 v[216:217], v[202:203], v[136:137], v[206:207] op_sel:[0,1,0]
	v_pk_fma_f32 v[218:219], v[204:205], v[136:137], v[208:209] op_sel:[0,1,0]
	v_pk_fma_f32 v[220:221], v[160:161], v[136:137], v[164:165] op_sel:[0,1,0]
	v_pk_fma_f32 v[222:223], v[162:163], v[136:137], v[166:167] op_sel:[0,1,0]
	v_pk_fma_f32 v[188:189], v[116:117], v[136:137], v[188:189] op_sel_hi:[1,0,1]
	v_pk_fma_f32 v[210:211], v[118:119], v[136:137], v[210:211] op_sel_hi:[1,0,1]
	v_pk_fma_f32 v[212:213], v[108:109], v[136:137], v[212:213] op_sel_hi:[1,0,1]
	v_pk_fma_f32 v[214:215], v[110:111], v[136:137], v[214:215] op_sel_hi:[1,0,1]
	v_pk_fma_f32 v[216:217], v[112:113], v[136:137], v[216:217] op_sel_hi:[1,0,1]
	v_pk_fma_f32 v[218:219], v[114:115], v[136:137], v[218:219] op_sel_hi:[1,0,1]
	v_pk_fma_f32 v[220:221], v[104:105], v[136:137], v[220:221] op_sel_hi:[1,0,1]
	v_pk_fma_f32 v[222:223], v[106:107], v[136:137], v[222:223] op_sel_hi:[1,0,1]
	v_pk_mul_f32 v[224:225], v[188:189], v[186:187] op_sel_hi:[1,0]
	v_pk_mul_f32 v[226:227], v[210:211], v[186:187] op_sel_hi:[1,0]
	v_pk_mul_f32 v[228:229], v[212:213], v[186:187] op_sel_hi:[1,0]
	v_pk_mul_f32 v[230:231], v[214:215], v[186:187] op_sel_hi:[1,0]
	v_exp_f32_e32 v224, v224
	v_exp_f32_e32 v225, v225
	v_exp_f32_e32 v226, v226
	v_exp_f32_e32 v227, v227
	v_exp_f32_e32 v228, v228
	v_exp_f32_e32 v229, v229
	v_exp_f32_e32 v230, v230
	v_exp_f32_e32 v231, v231
	v_pk_add_f32 v[224:225], v[224:225], v[186:187] op_sel:[0,1] op_sel_hi:[1,1]
	v_pk_add_f32 v[226:227], v[226:227], v[186:187] op_sel:[0,1] op_sel_hi:[1,1]
	v_pk_add_f32 v[228:229], v[228:229], v[186:187] op_sel:[0,1] op_sel_hi:[1,1]
	v_pk_add_f32 v[230:231], v[230:231], v[186:187] op_sel:[0,1] op_sel_hi:[1,1]
	v_rcp_f32_e32 v224, v224
	v_rcp_f32_e32 v225, v225
	v_rcp_f32_e32 v226, v226
	v_rcp_f32_e32 v227, v227
	v_rcp_f32_e32 v228, v228
	v_rcp_f32_e32 v229, v229
	v_rcp_f32_e32 v230, v230
	v_rcp_f32_e32 v231, v231
	v_pk_mul_f32 v[224:225], v[188:189], v[224:225]
	v_pk_mul_f32 v[226:227], v[210:211], v[226:227]
	v_pk_mul_f32 v[228:229], v[212:213], v[228:229]
	v_pk_mul_f32 v[230:231], v[214:215], v[230:231]
	v_pk_mul_f32 v[216:217], v[216:217], v[224:225]
	v_pk_mul_f32 v[218:219], v[218:219], v[226:227]
	v_pk_mul_f32 v[220:221], v[220:221], v[228:229]
	v_pk_mul_f32 v[222:223], v[222:223], v[230:231]
	v_cvt_pk_bf16_f32 v240, v216, v217
	v_cvt_pk_bf16_f32 v241, v218, v219
	v_cvt_pk_bf16_f32 v242, v220, v221
	v_cvt_pk_bf16_f32 v243, v222, v223
	v_lshl_add_u64 v[108:109], v[120:121], 0, v[142:143]
	global_store_dwordx4 v[108:109], v[240:243], off
	v_add_u32_e32 v104, 48, v200
	v_mad_i64_i32 v[104:105], s[40:41], v104, s88, v[184:185]
	v_pk_fma_f32 v[188:189], v[72:73], v[138:139], v[76:77] op_sel:[0,1,0]
	v_pk_fma_f32 v[210:211], v[74:75], v[138:139], v[78:79] op_sel:[0,1,0]
	v_pk_fma_f32 v[212:213], v[52:53], v[138:139], v[56:57] op_sel:[0,1,0]
	v_pk_fma_f32 v[214:215], v[54:55], v[138:139], v[58:59] op_sel:[0,1,0]
	v_pk_fma_f32 v[216:217], v[202:203], v[138:139], v[206:207] op_sel:[0,1,0]
	v_pk_fma_f32 v[218:219], v[204:205], v[138:139], v[208:209] op_sel:[0,1,0]
	v_pk_fma_f32 v[220:221], v[160:161], v[138:139], v[164:165] op_sel:[0,1,0]
	v_pk_fma_f32 v[222:223], v[162:163], v[138:139], v[166:167] op_sel:[0,1,0]
	v_pk_fma_f32 v[188:189], v[96:97], v[138:139], v[188:189] op_sel_hi:[1,0,1]
	v_pk_fma_f32 v[210:211], v[98:99], v[138:139], v[210:211] op_sel_hi:[1,0,1]
	v_pk_fma_f32 v[212:213], v[88:89], v[138:139], v[212:213] op_sel_hi:[1,0,1]
	v_pk_fma_f32 v[214:215], v[90:91], v[138:139], v[214:215] op_sel_hi:[1,0,1]
	v_pk_fma_f32 v[216:217], v[92:93], v[138:139], v[216:217] op_sel_hi:[1,0,1]
	v_pk_fma_f32 v[218:219], v[94:95], v[138:139], v[218:219] op_sel_hi:[1,0,1]
	v_pk_fma_f32 v[220:221], v[84:85], v[138:139], v[220:221] op_sel_hi:[1,0,1]
	v_pk_fma_f32 v[222:223], v[86:87], v[138:139], v[222:223] op_sel_hi:[1,0,1]
	v_pk_mul_f32 v[224:225], v[188:189], v[186:187] op_sel_hi:[1,0]
	v_pk_mul_f32 v[226:227], v[210:211], v[186:187] op_sel_hi:[1,0]
	v_pk_mul_f32 v[228:229], v[212:213], v[186:187] op_sel_hi:[1,0]
	v_pk_mul_f32 v[230:231], v[214:215], v[186:187] op_sel_hi:[1,0]
	v_exp_f32_e32 v224, v224
	v_exp_f32_e32 v225, v225
	v_exp_f32_e32 v226, v226
	v_exp_f32_e32 v227, v227
	v_exp_f32_e32 v228, v228
	v_exp_f32_e32 v229, v229
	v_exp_f32_e32 v230, v230
	v_exp_f32_e32 v231, v231
	v_pk_add_f32 v[224:225], v[224:225], v[186:187] op_sel:[0,1] op_sel_hi:[1,1]
	v_pk_add_f32 v[226:227], v[226:227], v[186:187] op_sel:[0,1] op_sel_hi:[1,1]
	v_pk_add_f32 v[228:229], v[228:229], v[186:187] op_sel:[0,1] op_sel_hi:[1,1]
	v_pk_add_f32 v[230:231], v[230:231], v[186:187] op_sel:[0,1] op_sel_hi:[1,1]
	v_rcp_f32_e32 v224, v224
	v_rcp_f32_e32 v225, v225
	v_rcp_f32_e32 v226, v226
	v_rcp_f32_e32 v227, v227
	v_rcp_f32_e32 v228, v228
	v_rcp_f32_e32 v229, v229
	v_rcp_f32_e32 v230, v230
	v_rcp_f32_e32 v231, v231
	v_pk_mul_f32 v[224:225], v[188:189], v[224:225]
	v_pk_mul_f32 v[226:227], v[210:211], v[226:227]
	v_pk_mul_f32 v[228:229], v[212:213], v[228:229]
	v_pk_mul_f32 v[230:231], v[214:215], v[230:231]
	v_pk_mul_f32 v[216:217], v[216:217], v[224:225]
	v_pk_mul_f32 v[218:219], v[218:219], v[226:227]
	v_pk_mul_f32 v[220:221], v[220:221], v[228:229]
	v_pk_mul_f32 v[222:223], v[222:223], v[230:231]
	v_cvt_pk_bf16_f32 v244, v216, v217
	v_cvt_pk_bf16_f32 v245, v218, v219
	v_cvt_pk_bf16_f32 v246, v220, v221
	v_cvt_pk_bf16_f32 v247, v222, v223
	v_lshl_add_u64 v[88:89], v[104:105], 0, v[142:143]
	global_store_dwordx4 v[88:89], v[244:247], off
	v_add_u32_e32 v84, 0x80, v200
	v_mad_i64_i32 v[84:85], s[40:41], v84, s88, v[184:185]
	v_pk_fma_f32 v[188:189], v[72:73], v[100:101], v[76:77] op_sel:[0,1,0]
	v_pk_fma_f32 v[210:211], v[74:75], v[100:101], v[78:79] op_sel:[0,1,0]
	v_pk_fma_f32 v[212:213], v[52:53], v[100:101], v[56:57] op_sel:[0,1,0]
	v_pk_fma_f32 v[214:215], v[54:55], v[100:101], v[58:59] op_sel:[0,1,0]
	v_pk_fma_f32 v[216:217], v[202:203], v[100:101], v[206:207] op_sel:[0,1,0]
	v_pk_fma_f32 v[218:219], v[204:205], v[100:101], v[208:209] op_sel:[0,1,0]
	v_pk_fma_f32 v[220:221], v[160:161], v[100:101], v[164:165] op_sel:[0,1,0]
	v_pk_fma_f32 v[222:223], v[162:163], v[100:101], v[166:167] op_sel:[0,1,0]
	v_pk_fma_f32 v[188:189], v[80:81], v[100:101], v[188:189] op_sel_hi:[1,0,1]
	v_pk_fma_f32 v[210:211], v[82:83], v[100:101], v[210:211] op_sel_hi:[1,0,1]
	v_pk_fma_f32 v[212:213], v[60:61], v[100:101], v[212:213] op_sel_hi:[1,0,1]
	v_pk_fma_f32 v[214:215], v[62:63], v[100:101], v[214:215] op_sel_hi:[1,0,1]
	v_pk_fma_f32 v[216:217], v[68:69], v[100:101], v[216:217] op_sel_hi:[1,0,1]
	v_pk_fma_f32 v[218:219], v[70:71], v[100:101], v[218:219] op_sel_hi:[1,0,1]
	v_pk_fma_f32 v[220:221], v[48:49], v[100:101], v[220:221] op_sel_hi:[1,0,1]
	v_pk_fma_f32 v[222:223], v[50:51], v[100:101], v[222:223] op_sel_hi:[1,0,1]
	v_pk_mul_f32 v[224:225], v[188:189], v[186:187] op_sel_hi:[1,0]
	v_pk_mul_f32 v[226:227], v[210:211], v[186:187] op_sel_hi:[1,0]
	v_pk_mul_f32 v[228:229], v[212:213], v[186:187] op_sel_hi:[1,0]
	v_pk_mul_f32 v[230:231], v[214:215], v[186:187] op_sel_hi:[1,0]
	v_exp_f32_e32 v224, v224
	v_exp_f32_e32 v225, v225
	v_exp_f32_e32 v226, v226
	v_exp_f32_e32 v227, v227
	v_exp_f32_e32 v228, v228
	v_exp_f32_e32 v229, v229
	v_exp_f32_e32 v230, v230
	v_exp_f32_e32 v231, v231
	v_pk_add_f32 v[224:225], v[224:225], v[186:187] op_sel:[0,1] op_sel_hi:[1,1]
	v_pk_add_f32 v[226:227], v[226:227], v[186:187] op_sel:[0,1] op_sel_hi:[1,1]
	v_pk_add_f32 v[228:229], v[228:229], v[186:187] op_sel:[0,1] op_sel_hi:[1,1]
	v_pk_add_f32 v[230:231], v[230:231], v[186:187] op_sel:[0,1] op_sel_hi:[1,1]
	v_rcp_f32_e32 v224, v224
	v_rcp_f32_e32 v225, v225
	v_rcp_f32_e32 v226, v226
	v_rcp_f32_e32 v227, v227
	v_rcp_f32_e32 v228, v228
	v_rcp_f32_e32 v229, v229
	v_rcp_f32_e32 v230, v230
	v_rcp_f32_e32 v231, v231
	v_pk_mul_f32 v[224:225], v[188:189], v[224:225]
	v_pk_mul_f32 v[226:227], v[210:211], v[226:227]
	v_pk_mul_f32 v[228:229], v[212:213], v[228:229]
	v_pk_mul_f32 v[230:231], v[214:215], v[230:231]
	v_pk_mul_f32 v[216:217], v[216:217], v[224:225]
	v_pk_mul_f32 v[218:219], v[218:219], v[226:227]
	v_pk_mul_f32 v[220:221], v[220:221], v[228:229]
	v_pk_mul_f32 v[222:223], v[222:223], v[230:231]
	v_cvt_pk_bf16_f32 v248, v216, v217
	v_cvt_pk_bf16_f32 v249, v218, v219
	v_cvt_pk_bf16_f32 v250, v220, v221
	v_cvt_pk_bf16_f32 v251, v222, v223
	v_lshl_add_u64 v[60:61], v[84:85], 0, v[142:143]
	global_store_dwordx4 v[60:61], v[248:251], off
	v_add_u32_e32 v48, 0x90, v200
	v_mad_i64_i32 v[48:49], s[40:41], v48, s88, v[184:185]
	v_pk_fma_f32 v[188:189], v[72:73], v[102:103], v[76:77] op_sel:[0,1,0]
	v_pk_fma_f32 v[210:211], v[74:75], v[102:103], v[78:79] op_sel:[0,1,0]
	v_pk_fma_f32 v[212:213], v[52:53], v[102:103], v[56:57] op_sel:[0,1,0]
	v_pk_fma_f32 v[214:215], v[54:55], v[102:103], v[58:59] op_sel:[0,1,0]
	v_pk_fma_f32 v[216:217], v[202:203], v[102:103], v[206:207] op_sel:[0,1,0]
	v_pk_fma_f32 v[218:219], v[204:205], v[102:103], v[208:209] op_sel:[0,1,0]
	v_pk_fma_f32 v[220:221], v[160:161], v[102:103], v[164:165] op_sel:[0,1,0]
	v_pk_fma_f32 v[222:223], v[162:163], v[102:103], v[166:167] op_sel:[0,1,0]
	v_pk_fma_f32 v[188:189], v[44:45], v[102:103], v[188:189] op_sel_hi:[1,0,1]
	v_pk_fma_f32 v[210:211], v[46:47], v[102:103], v[210:211] op_sel_hi:[1,0,1]
	v_pk_fma_f32 v[212:213], v[36:37], v[102:103], v[212:213] op_sel_hi:[1,0,1]
	v_pk_fma_f32 v[214:215], v[38:39], v[102:103], v[214:215] op_sel_hi:[1,0,1]
	v_pk_fma_f32 v[216:217], v[40:41], v[102:103], v[216:217] op_sel_hi:[1,0,1]
	v_pk_fma_f32 v[218:219], v[42:43], v[102:103], v[218:219] op_sel_hi:[1,0,1]
	v_pk_fma_f32 v[220:221], v[32:33], v[102:103], v[220:221] op_sel_hi:[1,0,1]
	v_pk_fma_f32 v[222:223], v[34:35], v[102:103], v[222:223] op_sel_hi:[1,0,1]
	v_pk_mul_f32 v[224:225], v[188:189], v[186:187] op_sel_hi:[1,0]
	v_pk_mul_f32 v[226:227], v[210:211], v[186:187] op_sel_hi:[1,0]
	v_pk_mul_f32 v[228:229], v[212:213], v[186:187] op_sel_hi:[1,0]
	v_pk_mul_f32 v[230:231], v[214:215], v[186:187] op_sel_hi:[1,0]
	v_exp_f32_e32 v224, v224
	v_exp_f32_e32 v225, v225
	v_exp_f32_e32 v226, v226
	v_exp_f32_e32 v227, v227
	v_exp_f32_e32 v228, v228
	v_exp_f32_e32 v229, v229
	v_exp_f32_e32 v230, v230
	v_exp_f32_e32 v231, v231
	v_pk_add_f32 v[224:225], v[224:225], v[186:187] op_sel:[0,1] op_sel_hi:[1,1]
	v_pk_add_f32 v[226:227], v[226:227], v[186:187] op_sel:[0,1] op_sel_hi:[1,1]
	v_pk_add_f32 v[228:229], v[228:229], v[186:187] op_sel:[0,1] op_sel_hi:[1,1]
	v_pk_add_f32 v[230:231], v[230:231], v[186:187] op_sel:[0,1] op_sel_hi:[1,1]
	v_rcp_f32_e32 v224, v224
	v_rcp_f32_e32 v225, v225
	v_rcp_f32_e32 v226, v226
	v_rcp_f32_e32 v227, v227
	v_rcp_f32_e32 v228, v228
	v_rcp_f32_e32 v229, v229
	v_rcp_f32_e32 v230, v230
	v_rcp_f32_e32 v231, v231
	v_pk_mul_f32 v[224:225], v[188:189], v[224:225]
	v_pk_mul_f32 v[226:227], v[210:211], v[226:227]
	v_pk_mul_f32 v[228:229], v[212:213], v[228:229]
	v_pk_mul_f32 v[230:231], v[214:215], v[230:231]
	v_pk_mul_f32 v[216:217], v[216:217], v[224:225]
	v_pk_mul_f32 v[218:219], v[218:219], v[226:227]
	v_pk_mul_f32 v[220:221], v[220:221], v[228:229]
	v_pk_mul_f32 v[222:223], v[222:223], v[230:231]
	v_cvt_pk_bf16_f32 v232, v216, v217
	v_cvt_pk_bf16_f32 v233, v218, v219
	v_cvt_pk_bf16_f32 v234, v220, v221
	v_cvt_pk_bf16_f32 v235, v222, v223
	v_lshl_add_u64 v[36:37], v[48:49], 0, v[142:143]
	global_store_dwordx4 v[36:37], v[232:235], off
	v_add_u32_e32 v32, 0xa0, v200
	v_mad_i64_i32 v[32:33], s[40:41], v32, s88, v[184:185]
	v_pk_fma_f32 v[188:189], v[72:73], v[64:65], v[76:77] op_sel:[0,1,0]
	v_pk_fma_f32 v[210:211], v[74:75], v[64:65], v[78:79] op_sel:[0,1,0]
	v_pk_fma_f32 v[212:213], v[52:53], v[64:65], v[56:57] op_sel:[0,1,0]
	v_pk_fma_f32 v[214:215], v[54:55], v[64:65], v[58:59] op_sel:[0,1,0]
	v_pk_fma_f32 v[216:217], v[202:203], v[64:65], v[206:207] op_sel:[0,1,0]
	v_pk_fma_f32 v[218:219], v[204:205], v[64:65], v[208:209] op_sel:[0,1,0]
	v_pk_fma_f32 v[220:221], v[160:161], v[64:65], v[164:165] op_sel:[0,1,0]
	v_pk_fma_f32 v[222:223], v[162:163], v[64:65], v[166:167] op_sel:[0,1,0]
	v_pk_fma_f32 v[188:189], v[28:29], v[64:65], v[188:189] op_sel_hi:[1,0,1]
	v_pk_fma_f32 v[210:211], v[30:31], v[64:65], v[210:211] op_sel_hi:[1,0,1]
	v_pk_fma_f32 v[212:213], v[20:21], v[64:65], v[212:213] op_sel_hi:[1,0,1]
	v_pk_fma_f32 v[214:215], v[22:23], v[64:65], v[214:215] op_sel_hi:[1,0,1]
	v_pk_fma_f32 v[216:217], v[24:25], v[64:65], v[216:217] op_sel_hi:[1,0,1]
	v_pk_fma_f32 v[218:219], v[26:27], v[64:65], v[218:219] op_sel_hi:[1,0,1]
	v_pk_fma_f32 v[220:221], v[16:17], v[64:65], v[220:221] op_sel_hi:[1,0,1]
	v_pk_fma_f32 v[222:223], v[18:19], v[64:65], v[222:223] op_sel_hi:[1,0,1]
	v_pk_mul_f32 v[224:225], v[188:189], v[186:187] op_sel_hi:[1,0]
	v_pk_mul_f32 v[226:227], v[210:211], v[186:187] op_sel_hi:[1,0]
	v_pk_mul_f32 v[228:229], v[212:213], v[186:187] op_sel_hi:[1,0]
	v_pk_mul_f32 v[230:231], v[214:215], v[186:187] op_sel_hi:[1,0]
	v_exp_f32_e32 v224, v224
	v_exp_f32_e32 v225, v225
	v_exp_f32_e32 v226, v226
	v_exp_f32_e32 v227, v227
	v_exp_f32_e32 v228, v228
	v_exp_f32_e32 v229, v229
	v_exp_f32_e32 v230, v230
	v_exp_f32_e32 v231, v231
	v_pk_add_f32 v[224:225], v[224:225], v[186:187] op_sel:[0,1] op_sel_hi:[1,1]
	v_pk_add_f32 v[226:227], v[226:227], v[186:187] op_sel:[0,1] op_sel_hi:[1,1]
	v_pk_add_f32 v[228:229], v[228:229], v[186:187] op_sel:[0,1] op_sel_hi:[1,1]
	v_pk_add_f32 v[230:231], v[230:231], v[186:187] op_sel:[0,1] op_sel_hi:[1,1]
	v_rcp_f32_e32 v224, v224
	v_rcp_f32_e32 v225, v225
	v_rcp_f32_e32 v226, v226
	v_rcp_f32_e32 v227, v227
	v_rcp_f32_e32 v228, v228
	v_rcp_f32_e32 v229, v229
	v_rcp_f32_e32 v230, v230
	v_rcp_f32_e32 v231, v231
	v_pk_mul_f32 v[224:225], v[188:189], v[224:225]
	v_pk_mul_f32 v[226:227], v[210:211], v[226:227]
	v_pk_mul_f32 v[228:229], v[212:213], v[228:229]
	v_pk_mul_f32 v[230:231], v[214:215], v[230:231]
	v_pk_mul_f32 v[216:217], v[216:217], v[224:225]
	v_pk_mul_f32 v[218:219], v[218:219], v[226:227]
	v_pk_mul_f32 v[220:221], v[220:221], v[228:229]
	v_pk_mul_f32 v[222:223], v[222:223], v[230:231]
	v_cvt_pk_bf16_f32 v236, v216, v217
	v_cvt_pk_bf16_f32 v237, v218, v219
	v_cvt_pk_bf16_f32 v238, v220, v221
	v_cvt_pk_bf16_f32 v239, v222, v223
	v_lshl_add_u64 v[20:21], v[32:33], 0, v[142:143]
	global_store_dwordx4 v[20:21], v[236:239], off
	v_add_u32_e32 v16, 0xb0, v200
	v_mad_i64_i32 v[16:17], s[40:41], v16, s88, v[184:185]
	s_nop 1
	s_mov_b64 s[40:41], -1
	v_pk_fma_f32 v[188:189], v[72:73], v[66:67], v[76:77] op_sel:[0,1,0]
	v_pk_fma_f32 v[210:211], v[74:75], v[66:67], v[78:79] op_sel:[0,1,0]
	v_pk_fma_f32 v[212:213], v[52:53], v[66:67], v[56:57] op_sel:[0,1,0]
	v_pk_fma_f32 v[214:215], v[54:55], v[66:67], v[58:59] op_sel:[0,1,0]
	v_pk_fma_f32 v[216:217], v[202:203], v[66:67], v[206:207] op_sel:[0,1,0]
	v_pk_fma_f32 v[218:219], v[204:205], v[66:67], v[208:209] op_sel:[0,1,0]
	v_pk_fma_f32 v[220:221], v[160:161], v[66:67], v[164:165] op_sel:[0,1,0]
	v_pk_fma_f32 v[222:223], v[162:163], v[66:67], v[166:167] op_sel:[0,1,0]
	v_pk_fma_f32 v[188:189], v[12:13], v[66:67], v[188:189] op_sel_hi:[1,0,1]
	v_pk_fma_f32 v[210:211], v[14:15], v[66:67], v[210:211] op_sel_hi:[1,0,1]
	v_pk_fma_f32 v[212:213], v[4:5], v[66:67], v[212:213] op_sel_hi:[1,0,1]
	v_pk_fma_f32 v[214:215], v[6:7], v[66:67], v[214:215] op_sel_hi:[1,0,1]
	v_pk_fma_f32 v[216:217], v[8:9], v[66:67], v[216:217] op_sel_hi:[1,0,1]
	v_pk_fma_f32 v[218:219], v[10:11], v[66:67], v[218:219] op_sel_hi:[1,0,1]
	v_pk_fma_f32 v[220:221], v[0:1], v[66:67], v[220:221] op_sel_hi:[1,0,1]
	v_pk_fma_f32 v[222:223], v[2:3], v[66:67], v[222:223] op_sel_hi:[1,0,1]
	v_pk_mul_f32 v[224:225], v[188:189], v[186:187] op_sel_hi:[1,0]
	v_pk_mul_f32 v[226:227], v[210:211], v[186:187] op_sel_hi:[1,0]
	v_pk_mul_f32 v[228:229], v[212:213], v[186:187] op_sel_hi:[1,0]
	v_pk_mul_f32 v[230:231], v[214:215], v[186:187] op_sel_hi:[1,0]
	v_exp_f32_e32 v224, v224
	v_exp_f32_e32 v225, v225
	v_exp_f32_e32 v226, v226
	v_exp_f32_e32 v227, v227
	v_exp_f32_e32 v228, v228
	v_exp_f32_e32 v229, v229
	v_exp_f32_e32 v230, v230
	v_exp_f32_e32 v231, v231
	v_pk_add_f32 v[224:225], v[224:225], v[186:187] op_sel:[0,1] op_sel_hi:[1,1]
	v_pk_add_f32 v[226:227], v[226:227], v[186:187] op_sel:[0,1] op_sel_hi:[1,1]
	v_pk_add_f32 v[228:229], v[228:229], v[186:187] op_sel:[0,1] op_sel_hi:[1,1]
	v_pk_add_f32 v[230:231], v[230:231], v[186:187] op_sel:[0,1] op_sel_hi:[1,1]
	v_rcp_f32_e32 v224, v224
	v_rcp_f32_e32 v225, v225
	v_rcp_f32_e32 v226, v226
	v_rcp_f32_e32 v227, v227
	v_rcp_f32_e32 v228, v228
	v_rcp_f32_e32 v229, v229
	v_rcp_f32_e32 v230, v230
	v_rcp_f32_e32 v231, v231
	v_pk_mul_f32 v[224:225], v[188:189], v[224:225]
	v_pk_mul_f32 v[226:227], v[210:211], v[226:227]
	v_pk_mul_f32 v[228:229], v[212:213], v[228:229]
	v_pk_mul_f32 v[230:231], v[214:215], v[230:231]
	v_pk_mul_f32 v[216:217], v[216:217], v[224:225]
	v_pk_mul_f32 v[218:219], v[218:219], v[226:227]
	v_pk_mul_f32 v[220:221], v[220:221], v[228:229]
	v_pk_mul_f32 v[222:223], v[222:223], v[230:231]
	v_cvt_pk_bf16_f32 v240, v216, v217
	v_cvt_pk_bf16_f32 v241, v218, v219
	v_cvt_pk_bf16_f32 v242, v220, v221
	v_cvt_pk_bf16_f32 v243, v222, v223
	v_lshl_add_u64 v[4:5], v[16:17], 0, v[142:143]
	global_store_dwordx4 v[4:5], v[240:243], off
	s_mov_b32 s99, 1
	s_cbranch_vccnz .LBB0_2464
	s_andn2_b64 vcc, exec, s[0:1]
	s_cbranch_vccnz .LBB0_2463
	s_barrier
	s_branch .LBB0_2463
